# strategy 9 loop-edge edit: the six K-loops' counter/pointer SALU updates and trip test hoisted above the closing s_barrier into the last MFMA group's shadow; only the branch stays behind the barrier
# baseline (speedup 1.0000x reference)
; #define PG8_STAGE(bufoff, gbase, voff) do { _Pragma("unroll") for (int _i = 0; _i < 2; ++_i) \
;         __builtin_amdgcn_global_load_lds((const unsigned*)((const char*)(gbase) + (voff)[_i]), (PG8_LAS unsigned*)(lds + (bufoff) + ldsw + _i * 8192), 16, 0, 0); } while (0)
; #define PG8_LDA(dst, b, h) do { _Pragma("unroll") for (int m = 0; m < 4; ++m) _Pragma("unroll") for (int k = 0; k < 2; ++k) dst[m][k] = *(const PG8_LAS bf16x8*)(lds + PG8_SA(b, h) + aoff + m * 2048 + k * 1024); } while (0)
; #define PG8_LDB(dst, b, h) do { _Pragma("unroll") for (int n = 0; n < 2; ++n) _Pragma("unroll") for (int k = 0; k < 2; ++k) dst[n][k] = *(const PG8_LAS bf16x8*)(lds + PG8_SB(b, h) + boff + n * 2048 + k * 1024); } while (0)
; #define PG8_MMA(ai, bj, At, Bt) do { __builtin_amdgcn_s_setprio(1); _Pragma("unroll") for (int m = 0; m < 4; ++m) _Pragma("unroll") for (int n = 0; n < 2; ++n) _Pragma("unroll") for (int k = 0; k < 2; ++k) \
;         acc[ai][bj][m][n] = __builtin_amdgcn_mfma_f32_16x16x32_bf16(Bt[n][k], At[m][k], acc[ai][bj][m][n], 0, 0, 0); __builtin_amdgcn_s_setprio(0); } while (0)
; #define PG8_WAIT_V(n) asm volatile("s_waitcnt vmcnt(" #n ")" ::: "memory")
; #define PG8_WAIT_L(n) asm volatile("s_waitcnt lgkmcnt(" #n ")" ::: "memory")
; #define PG8_BAR __builtin_amdgcn_s_barrier()
; #define PG8_SCHED __builtin_amdgcn_sched_barrier(0)
; template <class Epi, class Sched, bool ALIGN_EPI = false, bool SP2 = false>
; __device__ __forceinline__ void gemm_phase(PG8_LAS unsigned char* lds, const Gemm g, const Sched& S, const Epi& E, const int tid) {
;     ...
;             const bool last = (t == nt - 2);
;             const char* a1 = cA + (size_t)(t + 1) * kstep;
;             const char* a2 = last ? nA : cA + (size_t)(t + 2) * kstep; const char* b2 = last ? nB : cB + (size_t)(t + 2) * kstep;
;             const char* a3 = a2 + kstep; const char* b3 = b2 + kstep;
;             if (last && has_next) S.a_ready(nxt);
;             if constexpr (SP2) {
;             PG8_LDB(B0, 0, 0); PG8_LDB(B1, 0, 1); PG8_SCHED; PG8_LDA(At, 0, 0); PG8_STAGE(PG8_SA(1, 1), a1 + hstep, voffA);
;             PG8_WAIT_V(8); PG8_WAIT_L(0); PG8_BAR; PG8_MMA(0, 0, At, B0); PG8_MMA(0, 1, At, B1); PG8_BAR; PG8_SCHED;
;             PG8_LDA(At, 0, 1); PG8_STAGE(PG8_SB(0, 0), b2, voffB); PG8_STAGE(PG8_SB(0, 1), b2 + hstep, voffB); PG8_STAGE(PG8_SA(0, 0), a2, voffA);
.LBB0_94:
	s_add_u32 s35, s52, 0xfffc0080
	s_addc_u32 s43, s53, -1
	s_add_i32 s45, 0, 0x10000
	s_cmp_eq_u32 s34, 12
	s_cselect_b32 s57, s0, s43
	s_cselect_b32 s56, s1, s35
	s_waitcnt lgkmcnt(0)
	v_add_u32_e32 v156, s45, v5
	s_cselect_b32 s55, s9, s33
	s_cselect_b32 s54, s18, s19
	s_add_i32 s35, 0, 0x14000
	ds_read_b128 v[134:137], v156
	ds_read_b128 v[138:141], v156 offset:1024
	ds_read_b128 v[152:155], v156 offset:2048
	ds_read_b128 v[164:167], v156 offset:3072
	v_add_u32_e32 v156, s35, v5
	ds_read_b128 v[168:171], v156
	ds_read_b128 v[172:175], v156 offset:1024
	ds_read_b128 v[194:197], v156 offset:2048
	ds_read_b128 v[198:201], v156 offset:3072
	v_lshl_add_u64 v[156:157], s[52:53], 0, v[148:149]
	s_add_i32 m0, s61, 0xc000
	ds_read_b128 v[202:205], v191
	ds_read_b128 v[206:209], v191 offset:1024
	ds_read_b128 v[210:213], v191 offset:2048
	ds_read_b128 v[218:221], v191 offset:3072
	ds_read_b128 v[222:225], v191 offset:4096
	ds_read_b128 v[226:229], v191 offset:5120
	ds_read_b128 v[230:233], v191 offset:6144
	ds_read_b128 v[234:237], v191 offset:7168
	global_load_lds_dwordx4 v[156:157], off
	v_lshl_add_u64 v[156:157], s[52:53], 0, v[150:151]
	s_add_i32 m0, s61, 0xe000
	s_nop 0
	global_load_lds_dwordx4 v[156:157], off
	s_waitcnt vmcnt(8)
	s_waitcnt lgkmcnt(0)
	s_barrier
	s_waitcnt lgkmcnt(0)
	v_mfma_f32_16x16x32_bf16 v[130:133], v[134:137], v[202:205], v[130:133]
	v_mfma_f32_16x16x32_bf16 v[126:129], v[152:155], v[202:205], v[126:129]
	v_mfma_f32_16x16x32_bf16 v[114:117], v[134:137], v[210:213], v[114:117]
	v_mfma_f32_16x16x32_bf16 v[110:113], v[152:155], v[210:213], v[110:113]
	v_mfma_f32_16x16x32_bf16 v[98:101], v[134:137], v[222:225], v[98:101]
	v_mfma_f32_16x16x32_bf16 v[94:97], v[152:155], v[222:225], v[94:97]
	v_mfma_f32_16x16x32_bf16 v[82:85], v[134:137], v[230:233], v[82:85]
	v_mfma_f32_16x16x32_bf16 v[78:81], v[152:155], v[230:233], v[78:81]
	v_mfma_f32_16x16x32_bf16 v[130:133], v[138:141], v[206:209], v[130:133]
	v_mfma_f32_16x16x32_bf16 v[126:129], v[164:167], v[206:209], v[126:129]
	v_mfma_f32_16x16x32_bf16 v[114:117], v[138:141], v[218:221], v[114:117]
	v_mfma_f32_16x16x32_bf16 v[110:113], v[164:167], v[218:221], v[110:113]
	v_mfma_f32_16x16x32_bf16 v[98:101], v[138:141], v[226:229], v[98:101]
	v_mfma_f32_16x16x32_bf16 v[94:97], v[164:167], v[226:229], v[94:97]
	v_mfma_f32_16x16x32_bf16 v[82:85], v[138:141], v[234:237], v[82:85]
	v_mfma_f32_16x16x32_bf16 v[78:81], v[164:167], v[234:237], v[78:81]
	v_mfma_f32_16x16x32_bf16 v[122:125], v[168:171], v[202:205], v[122:125]
	v_mfma_f32_16x16x32_bf16 v[118:121], v[194:197], v[202:205], v[118:121]
	v_mfma_f32_16x16x32_bf16 v[106:109], v[168:171], v[210:213], v[106:109]
	v_mfma_f32_16x16x32_bf16 v[102:105], v[194:197], v[210:213], v[102:105]
	v_mfma_f32_16x16x32_bf16 v[90:93], v[168:171], v[222:225], v[90:93]
	v_mfma_f32_16x16x32_bf16 v[86:89], v[194:197], v[222:225], v[86:89]
	v_mfma_f32_16x16x32_bf16 v[74:77], v[168:171], v[230:233], v[74:77]
	v_mfma_f32_16x16x32_bf16 v[70:73], v[194:197], v[230:233], v[70:73]
	v_mfma_f32_16x16x32_bf16 v[122:125], v[172:175], v[206:209], v[122:125]
	v_mfma_f32_16x16x32_bf16 v[118:121], v[198:201], v[206:209], v[118:121]
	v_mfma_f32_16x16x32_bf16 v[106:109], v[172:175], v[218:221], v[106:109]
	v_mfma_f32_16x16x32_bf16 v[102:105], v[198:201], v[218:221], v[102:105]
	v_mfma_f32_16x16x32_bf16 v[90:93], v[172:175], v[226:229], v[90:93]
	v_mfma_f32_16x16x32_bf16 v[86:89], v[198:201], v[226:229], v[86:89]
	v_mfma_f32_16x16x32_bf16 v[74:77], v[172:175], v[234:237], v[74:77]
	v_mfma_f32_16x16x32_bf16 v[70:73], v[198:201], v[234:237], v[70:73]
	s_barrier
	s_add_i32 s43, s45, s60
	v_lshl_add_u64 v[156:157], s[54:55], 0, v[142:143]
	s_mov_b32 m0, s43
	ds_read_b128 v[202:205], v191 offset:16384
	ds_read_b128 v[206:209], v191 offset:17408
	ds_read_b128 v[210:213], v191 offset:18432
	ds_read_b128 v[218:221], v191 offset:19456
	ds_read_b128 v[222:225], v191 offset:20480
	ds_read_b128 v[226:229], v191 offset:21504
	ds_read_b128 v[230:233], v191 offset:22528
	ds_read_b128 v[234:237], v191 offset:23552
	global_load_lds_dwordx4 v[156:157], off
	s_add_i32 m0, s43, 0x2000
	s_add_u32 s70, s54, 0x40000
	v_lshl_add_u64 v[176:177], s[54:55], 0, v[146:147]
	s_addc_u32 s71, s55, 0
	s_add_i32 s35, s35, s60
	global_load_lds_dwordx4 v[176:177], off
	v_lshl_add_u64 v[238:239], s[70:71], 0, v[142:143]
	s_mov_b32 m0, s35
	v_lshl_add_u64 v[240:241], s[56:57], 0, v[144:145]
	global_load_lds_dwordx4 v[238:239], off
	v_lshl_add_u64 v[238:239], s[70:71], 0, v[146:147]
	s_add_i32 m0, s35, 0x2000
	s_nop 0
	global_load_lds_dwordx4 v[238:239], off
	v_lshl_add_u64 v[238:239], s[56:57], 0, v[2:3]
	s_mov_b32 m0, s61
	s_nop 0
	global_load_lds_dwordx4 v[238:239], off
	s_mov_b32 m0, s62
	s_nop 0
	global_load_lds_dwordx4 v[240:241], off
	s_waitcnt vmcnt(8)
	s_waitcnt lgkmcnt(0)
	s_barrier
; #define PG8_STAGE(bufoff, gbase, voff) do { _Pragma("unroll") for (int _i = 0; _i < 2; ++_i) \
;         __builtin_amdgcn_global_load_lds((const unsigned*)((const char*)(gbase) + (voff)[_i]), (PG8_LAS unsigned*)(lds + (bufoff) + ldsw + _i * 8192), 16, 0, 0); } while (0)
; #define PG8_LDA(dst, b, h) do { _Pragma("unroll") for (int m = 0; m < 4; ++m) _Pragma("unroll") for (int k = 0; k < 2; ++k) dst[m][k] = *(const PG8_LAS bf16x8*)(lds + PG8_SA(b, h) + aoff + m * 2048 + k * 1024); } while (0)
; #define PG8_LDB(dst, b, h) do { _Pragma("unroll") for (int n = 0; n < 2; ++n) _Pragma("unroll") for (int k = 0; k < 2; ++k) dst[n][k] = *(const PG8_LAS bf16x8*)(lds + PG8_SB(b, h) + boff + n * 2048 + k * 1024); } while (0)
; #define PG8_MMA(ai, bj, At, Bt) do { __builtin_amdgcn_s_setprio(1); _Pragma("unroll") for (int m = 0; m < 4; ++m) _Pragma("unroll") for (int n = 0; n < 2; ++n) _Pragma("unroll") for (int k = 0; k < 2; ++k) \
;         acc[ai][bj][m][n] = __builtin_amdgcn_mfma_f32_16x16x32_bf16(Bt[n][k], At[m][k], acc[ai][bj][m][n], 0, 0, 0); __builtin_amdgcn_s_setprio(0); } while (0)
; #define PG8_WAIT_V(n) asm volatile("s_waitcnt vmcnt(" #n ")" ::: "memory")
; #define PG8_WAIT_L(n) asm volatile("s_waitcnt lgkmcnt(" #n ")" ::: "memory")
; #define PG8_BAR __builtin_amdgcn_s_barrier()
; #define PG8_SCHED __builtin_amdgcn_sched_barrier(0)
; template <class Epi, class Sched, bool ALIGN_EPI = false, bool SP2 = false>
; __device__ __forceinline__ void gemm_phase(PG8_LAS unsigned char* lds, const Gemm g, const Sched& S, const Epi& E, const int tid) {
;     ...
;             PG8_WAIT_V(8); PG8_WAIT_L(0); PG8_BAR; PG8_MMA(1, 0, At, B0); PG8_MMA(1, 1, At, B1); PG8_BAR; PG8_SCHED;
;             PG8_LDB(B0, 1, 0); PG8_LDB(B1, 1, 1); PG8_SCHED; PG8_LDA(At, 1, 0); PG8_STAGE(PG8_SA(0, 1), a2 + hstep, voffA);
;             PG8_WAIT_V(8); PG8_WAIT_L(0); PG8_BAR; PG8_MMA(0, 0, At, B0); PG8_MMA(0, 1, At, B1); PG8_BAR; PG8_SCHED;
	s_waitcnt lgkmcnt(0)
	v_mfma_f32_16x16x32_bf16 v[66:69], v[134:137], v[202:205], v[66:69]
	v_mfma_f32_16x16x32_bf16 v[62:65], v[152:155], v[202:205], v[62:65]
	v_mfma_f32_16x16x32_bf16 v[50:53], v[134:137], v[210:213], v[50:53]
	v_mfma_f32_16x16x32_bf16 v[46:49], v[152:155], v[210:213], v[46:49]
	v_mfma_f32_16x16x32_bf16 v[34:37], v[134:137], v[222:225], v[34:37]
	v_mfma_f32_16x16x32_bf16 v[30:33], v[152:155], v[222:225], v[30:33]
	v_mfma_f32_16x16x32_bf16 v[18:21], v[134:137], v[230:233], v[18:21]
	v_mfma_f32_16x16x32_bf16 v[14:17], v[152:155], v[230:233], v[14:17]
	v_mfma_f32_16x16x32_bf16 v[66:69], v[138:141], v[206:209], v[66:69]
	v_mfma_f32_16x16x32_bf16 v[62:65], v[164:167], v[206:209], v[62:65]
	v_mfma_f32_16x16x32_bf16 v[50:53], v[138:141], v[218:221], v[50:53]
	v_mfma_f32_16x16x32_bf16 v[46:49], v[164:167], v[218:221], v[46:49]
	v_mfma_f32_16x16x32_bf16 v[34:37], v[138:141], v[226:229], v[34:37]
	v_mfma_f32_16x16x32_bf16 v[30:33], v[164:167], v[226:229], v[30:33]
	v_mfma_f32_16x16x32_bf16 v[18:21], v[138:141], v[234:237], v[18:21]
	v_mfma_f32_16x16x32_bf16 v[14:17], v[164:167], v[234:237], v[14:17]
	v_mfma_f32_16x16x32_bf16 v[58:61], v[168:171], v[202:205], v[58:61]
	v_mfma_f32_16x16x32_bf16 v[54:57], v[194:197], v[202:205], v[54:57]
	v_mfma_f32_16x16x32_bf16 v[42:45], v[168:171], v[210:213], v[42:45]
	v_mfma_f32_16x16x32_bf16 v[38:41], v[194:197], v[210:213], v[38:41]
	v_mfma_f32_16x16x32_bf16 v[26:29], v[168:171], v[222:225], v[26:29]
	v_mfma_f32_16x16x32_bf16 v[22:25], v[194:197], v[222:225], v[22:25]
	v_mfma_f32_16x16x32_bf16 v[10:13], v[168:171], v[230:233], v[10:13]
	v_mfma_f32_16x16x32_bf16 v[6:9], v[194:197], v[230:233], v[6:9]
	v_mfma_f32_16x16x32_bf16 v[58:61], v[172:175], v[206:209], v[58:61]
	v_mfma_f32_16x16x32_bf16 v[54:57], v[198:201], v[206:209], v[54:57]
	v_mfma_f32_16x16x32_bf16 v[42:45], v[172:175], v[218:221], v[42:45]
	v_mfma_f32_16x16x32_bf16 v[38:41], v[198:201], v[218:221], v[38:41]
	v_mfma_f32_16x16x32_bf16 v[26:29], v[172:175], v[226:229], v[26:29]
	v_mfma_f32_16x16x32_bf16 v[22:25], v[198:201], v[226:229], v[22:25]
	v_mfma_f32_16x16x32_bf16 v[10:13], v[172:175], v[234:237], v[10:13]
	v_mfma_f32_16x16x32_bf16 v[6:9], v[198:201], v[234:237], v[6:9]
	s_barrier
	s_add_i32 s35, 0, 0x18000
	v_add_u32_e32 v160, s35, v5
	s_add_i32 s43, 0, 0x1c000
	ds_read_b128 v[134:137], v160
	ds_read_b128 v[138:141], v160 offset:1024
	ds_read_b128 v[152:155], v160 offset:2048
	ds_read_b128 v[164:167], v160 offset:3072
	v_add_u32_e32 v160, s43, v5
	ds_read_b128 v[168:171], v160
	ds_read_b128 v[172:175], v160 offset:1024
	ds_read_b128 v[194:197], v160 offset:2048
	ds_read_b128 v[198:201], v160 offset:3072
	s_add_u32 s56, s56, 0x40000
	s_addc_u32 s57, s57, 0
	s_mov_b32 m0, s63
	v_lshl_add_u64 v[242:243], s[56:57], 0, v[2:3]
	ds_read_b128 v[202:205], v191 offset:32768
	ds_read_b128 v[206:209], v191 offset:33792
	ds_read_b128 v[210:213], v191 offset:34816
	ds_read_b128 v[218:221], v191 offset:35840
	ds_read_b128 v[222:225], v191 offset:36864
	ds_read_b128 v[226:229], v191 offset:37888
	ds_read_b128 v[230:233], v191 offset:38912
	ds_read_b128 v[234:237], v191 offset:39936
	global_load_lds_dwordx4 v[242:243], off
	v_lshl_add_u64 v[242:243], s[56:57], 0, v[144:145]
	s_mov_b32 m0, s64
	s_nop 0
	global_load_lds_dwordx4 v[242:243], off
	s_waitcnt vmcnt(8)
	s_waitcnt lgkmcnt(0)
	s_barrier
	s_waitcnt lgkmcnt(0)
	v_mfma_f32_16x16x32_bf16 v[130:133], v[134:137], v[202:205], v[130:133]
	v_mfma_f32_16x16x32_bf16 v[126:129], v[152:155], v[202:205], v[126:129]
	v_mfma_f32_16x16x32_bf16 v[114:117], v[134:137], v[210:213], v[114:117]
	v_mfma_f32_16x16x32_bf16 v[110:113], v[152:155], v[210:213], v[110:113]
	v_mfma_f32_16x16x32_bf16 v[98:101], v[134:137], v[222:225], v[98:101]
	v_mfma_f32_16x16x32_bf16 v[94:97], v[152:155], v[222:225], v[94:97]
	v_mfma_f32_16x16x32_bf16 v[82:85], v[134:137], v[230:233], v[82:85]
	v_mfma_f32_16x16x32_bf16 v[78:81], v[152:155], v[230:233], v[78:81]
	v_mfma_f32_16x16x32_bf16 v[130:133], v[138:141], v[206:209], v[130:133]
	v_mfma_f32_16x16x32_bf16 v[126:129], v[164:167], v[206:209], v[126:129]
	v_mfma_f32_16x16x32_bf16 v[114:117], v[138:141], v[218:221], v[114:117]
	v_mfma_f32_16x16x32_bf16 v[110:113], v[164:167], v[218:221], v[110:113]
	v_mfma_f32_16x16x32_bf16 v[98:101], v[138:141], v[226:229], v[98:101]
	v_mfma_f32_16x16x32_bf16 v[94:97], v[164:167], v[226:229], v[94:97]
	v_mfma_f32_16x16x32_bf16 v[82:85], v[138:141], v[234:237], v[82:85]
	v_mfma_f32_16x16x32_bf16 v[78:81], v[164:167], v[234:237], v[78:81]
	v_mfma_f32_16x16x32_bf16 v[122:125], v[168:171], v[202:205], v[122:125]
	v_mfma_f32_16x16x32_bf16 v[118:121], v[194:197], v[202:205], v[118:121]
	v_mfma_f32_16x16x32_bf16 v[106:109], v[168:171], v[210:213], v[106:109]
	v_mfma_f32_16x16x32_bf16 v[102:105], v[194:197], v[210:213], v[102:105]
	v_mfma_f32_16x16x32_bf16 v[90:93], v[168:171], v[222:225], v[90:93]
	v_mfma_f32_16x16x32_bf16 v[86:89], v[194:197], v[222:225], v[86:89]
	v_mfma_f32_16x16x32_bf16 v[74:77], v[168:171], v[230:233], v[74:77]
	v_mfma_f32_16x16x32_bf16 v[70:73], v[194:197], v[230:233], v[70:73]
	v_mfma_f32_16x16x32_bf16 v[122:125], v[172:175], v[206:209], v[122:125]
	v_mfma_f32_16x16x32_bf16 v[118:121], v[198:201], v[206:209], v[118:121]
	v_mfma_f32_16x16x32_bf16 v[106:109], v[172:175], v[218:221], v[106:109]
	v_mfma_f32_16x16x32_bf16 v[102:105], v[198:201], v[218:221], v[102:105]
	v_mfma_f32_16x16x32_bf16 v[90:93], v[172:175], v[226:229], v[90:93]
	v_mfma_f32_16x16x32_bf16 v[86:89], v[198:201], v[226:229], v[86:89]
	v_mfma_f32_16x16x32_bf16 v[74:77], v[172:175], v[234:237], v[74:77]
	v_mfma_f32_16x16x32_bf16 v[70:73], v[198:201], v[234:237], v[70:73]
	s_barrier
; #define PG8_STAGE(bufoff, gbase, voff) do { _Pragma("unroll") for (int _i = 0; _i < 2; ++_i) \
;         __builtin_amdgcn_global_load_lds((const unsigned*)((const char*)(gbase) + (voff)[_i]), (PG8_LAS unsigned*)(lds + (bufoff) + ldsw + _i * 8192), 16, 0, 0); } while (0)
; #define PG8_LDA(dst, b, h) do { _Pragma("unroll") for (int m = 0; m < 4; ++m) _Pragma("unroll") for (int k = 0; k < 2; ++k) dst[m][k] = *(const PG8_LAS bf16x8*)(lds + PG8_SA(b, h) + aoff + m * 2048 + k * 1024); } while (0)
; #define PG8_MMA(ai, bj, At, Bt) do { __builtin_amdgcn_s_setprio(1); _Pragma("unroll") for (int m = 0; m < 4; ++m) _Pragma("unroll") for (int n = 0; n < 2; ++n) _Pragma("unroll") for (int k = 0; k < 2; ++k) \
;         acc[ai][bj][m][n] = __builtin_amdgcn_mfma_f32_16x16x32_bf16(Bt[n][k], At[m][k], acc[ai][bj][m][n], 0, 0, 0); __builtin_amdgcn_s_setprio(0); } while (0)
; #define PG8_WAIT_V(n) asm volatile("s_waitcnt vmcnt(" #n ")" ::: "memory")
; #define PG8_WAIT_L(n) asm volatile("s_waitcnt lgkmcnt(" #n ")" ::: "memory")
; #define PG8_BAR __builtin_amdgcn_s_barrier()
; #define PG8_SCHED __builtin_amdgcn_sched_barrier(0)
; template <class Epi, class Sched, bool ALIGN_EPI = false, bool SP2 = false>
; __device__ __forceinline__ void gemm_phase(PG8_LAS unsigned char* lds, const Gemm g, const Sched& S, const Epi& E, const int tid) {
;     ...
;             PG8_LDA(At, 1, 1); PG8_STAGE(PG8_SB(1, 0), b3, voffB); PG8_STAGE(PG8_SB(1, 1), b3 + hstep, voffB); PG8_STAGE(PG8_SA(1, 0), a3, voffA);
;             PG8_WAIT_V(8); PG8_WAIT_L(0); PG8_BAR; PG8_MMA(1, 0, At, B0); PG8_MMA(1, 1, At, B1); PG8_BAR; PG8_SCHED;
;     ...
;         if constexpr (ALIGN_EPI) { if (wr == 0) PG8_BAR; }
	s_add_i32 s35, s35, s60
	v_lshl_add_u64 v[156:157], v[156:157], 0, s[16:17]
	s_mov_b32 m0, s35
	ds_read_b128 v[202:205], v191 offset:49152
	ds_read_b128 v[206:209], v191 offset:50176
	ds_read_b128 v[210:213], v191 offset:51200
	ds_read_b128 v[218:221], v191 offset:52224
	ds_read_b128 v[222:225], v191 offset:53248
	ds_read_b128 v[226:229], v191 offset:54272
	ds_read_b128 v[230:233], v191 offset:55296
	ds_read_b128 v[234:237], v191 offset:56320
	global_load_lds_dwordx4 v[156:157], off
	s_add_i32 m0, s35, 0x2000
	s_add_u32 s54, s54, 0x40080
	v_lshl_add_u64 v[156:157], v[176:177], 0, s[16:17]
	s_addc_u32 s55, s55, 0
	s_add_i32 s35, s43, s60
	global_load_lds_dwordx4 v[156:157], off
	v_lshl_add_u64 v[156:157], s[54:55], 0, v[142:143]
	s_mov_b32 m0, s35
	s_nop 0
	global_load_lds_dwordx4 v[156:157], off
	v_lshl_add_u64 v[156:157], s[54:55], 0, v[146:147]
	s_add_i32 m0, s35, 0x2000
	s_nop 0
	global_load_lds_dwordx4 v[156:157], off
	v_lshl_add_u64 v[156:157], v[238:239], 0, s[16:17]
	s_mov_b32 m0, s20
	s_nop 0
	global_load_lds_dwordx4 v[156:157], off
	v_lshl_add_u64 v[156:157], v[240:241], 0, s[16:17]
	s_mov_b32 m0, s65
	s_nop 0
	global_load_lds_dwordx4 v[156:157], off
	s_waitcnt vmcnt(8)
	s_waitcnt lgkmcnt(0)
	s_barrier
	s_waitcnt lgkmcnt(0)
	v_mfma_f32_16x16x32_bf16 v[66:69], v[134:137], v[202:205], v[66:69]
	v_mfma_f32_16x16x32_bf16 v[62:65], v[152:155], v[202:205], v[62:65]
	v_mfma_f32_16x16x32_bf16 v[50:53], v[134:137], v[210:213], v[50:53]
	v_mfma_f32_16x16x32_bf16 v[46:49], v[152:155], v[210:213], v[46:49]
	v_mfma_f32_16x16x32_bf16 v[34:37], v[134:137], v[222:225], v[34:37]
	v_mfma_f32_16x16x32_bf16 v[30:33], v[152:155], v[222:225], v[30:33]
	v_mfma_f32_16x16x32_bf16 v[18:21], v[134:137], v[230:233], v[18:21]
	v_mfma_f32_16x16x32_bf16 v[14:17], v[152:155], v[230:233], v[14:17]
	v_mfma_f32_16x16x32_bf16 v[66:69], v[138:141], v[206:209], v[66:69]
	v_mfma_f32_16x16x32_bf16 v[62:65], v[164:167], v[206:209], v[62:65]
	v_mfma_f32_16x16x32_bf16 v[50:53], v[138:141], v[218:221], v[50:53]
	v_mfma_f32_16x16x32_bf16 v[46:49], v[164:167], v[218:221], v[46:49]
	v_mfma_f32_16x16x32_bf16 v[34:37], v[138:141], v[226:229], v[34:37]
	v_mfma_f32_16x16x32_bf16 v[30:33], v[164:167], v[226:229], v[30:33]
	v_mfma_f32_16x16x32_bf16 v[18:21], v[138:141], v[234:237], v[18:21]
	v_mfma_f32_16x16x32_bf16 v[14:17], v[164:167], v[234:237], v[14:17]
	v_mfma_f32_16x16x32_bf16 v[58:61], v[168:171], v[202:205], v[58:61]
	v_mfma_f32_16x16x32_bf16 v[54:57], v[194:197], v[202:205], v[54:57]
	v_mfma_f32_16x16x32_bf16 v[42:45], v[168:171], v[210:213], v[42:45]
	v_mfma_f32_16x16x32_bf16 v[38:41], v[194:197], v[210:213], v[38:41]
	v_mfma_f32_16x16x32_bf16 v[26:29], v[168:171], v[222:225], v[26:29]
	v_mfma_f32_16x16x32_bf16 v[22:25], v[194:197], v[222:225], v[22:25]
	v_mfma_f32_16x16x32_bf16 v[10:13], v[168:171], v[230:233], v[10:13]
	v_mfma_f32_16x16x32_bf16 v[6:9], v[194:197], v[230:233], v[6:9]
	v_mfma_f32_16x16x32_bf16 v[58:61], v[172:175], v[206:209], v[58:61]
	v_mfma_f32_16x16x32_bf16 v[54:57], v[198:201], v[206:209], v[54:57]
	v_mfma_f32_16x16x32_bf16 v[42:45], v[172:175], v[218:221], v[42:45]
	v_mfma_f32_16x16x32_bf16 v[38:41], v[198:201], v[218:221], v[38:41]
	v_mfma_f32_16x16x32_bf16 v[26:29], v[172:175], v[226:229], v[26:29]
	v_mfma_f32_16x16x32_bf16 v[22:25], v[198:201], v[226:229], v[22:25]
	v_mfma_f32_16x16x32_bf16 v[10:13], v[172:175], v[234:237], v[10:13]
	v_mfma_f32_16x16x32_bf16 v[6:9], v[198:201], v[234:237], v[6:9]
	s_add_i32 s34, s34, 2
	s_add_u32 s52, s52, 0x100
	s_addc_u32 s53, s53, 0
	s_add_u32 s19, s19, 0x100
	s_addc_u32 s33, s33, 0
	s_cmp_gt_u32 s34, 13
	s_barrier
	s_cbranch_scc0 .LBB0_94
	s_and_b64 vcc, exec, s[40:41]
	s_cbranch_vccz .LBB0_97
	s_barrier

; #define PG8_STAGE(bufoff, gbase, voff) do { _Pragma("unroll") for (int _i = 0; _i < 2; ++_i) \
;         __builtin_amdgcn_global_load_lds((const unsigned*)((const char*)(gbase) + (voff)[_i]), (PG8_LAS unsigned*)(lds + (bufoff) + ldsw + _i * 8192), 16, 0, 0); } while (0)
; #define PG8_LDA(dst, b, h) do { _Pragma("unroll") for (int m = 0; m < 4; ++m) _Pragma("unroll") for (int k = 0; k < 2; ++k) dst[m][k] = *(const PG8_LAS bf16x8*)(lds + PG8_SA(b, h) + aoff + m * 2048 + k * 1024); } while (0)
; #define PG8_LDB(dst, b, h) do { _Pragma("unroll") for (int n = 0; n < 2; ++n) _Pragma("unroll") for (int k = 0; k < 2; ++k) dst[n][k] = *(const PG8_LAS bf16x8*)(lds + PG8_SB(b, h) + boff + n * 2048 + k * 1024); } while (0)
; #define PG8_MMA(ai, bj, At, Bt) do { __builtin_amdgcn_s_setprio(1); _Pragma("unroll") for (int m = 0; m < 4; ++m) _Pragma("unroll") for (int n = 0; n < 2; ++n) _Pragma("unroll") for (int k = 0; k < 2; ++k) \
;         acc[ai][bj][m][n] = __builtin_amdgcn_mfma_f32_16x16x32_bf16(Bt[n][k], At[m][k], acc[ai][bj][m][n], 0, 0, 0); __builtin_amdgcn_s_setprio(0); } while (0)
; #define PG8_WAIT_V(n) asm volatile("s_waitcnt vmcnt(" #n ")" ::: "memory")
; #define PG8_WAIT_L(n) asm volatile("s_waitcnt lgkmcnt(" #n ")" ::: "memory")
; #define PG8_BAR __builtin_amdgcn_s_barrier()
; #define PG8_SCHED __builtin_amdgcn_sched_barrier(0)
; template <class Epi, class Sched, bool ALIGN_EPI = false, bool SP2 = false>
; __device__ __forceinline__ void gemm_phase(PG8_LAS unsigned char* lds, const Gemm g, const Sched& S, const Epi& E, const int tid) {
;     ...
;             const bool last = (t == nt - 2);
;             const char* a1 = cA + (size_t)(t + 1) * kstep;
;             const char* a2 = last ? nA : cA + (size_t)(t + 2) * kstep; const char* b2 = last ? nB : cB + (size_t)(t + 2) * kstep;
;             const char* a3 = a2 + kstep; const char* b3 = b2 + kstep;
;             if (last && has_next) S.a_ready(nxt);
;             if constexpr (SP2) {
;             PG8_LDB(B0, 0, 0); PG8_LDB(B1, 0, 1); PG8_SCHED; PG8_LDA(At, 0, 0); PG8_STAGE(PG8_SA(1, 1), a1 + hstep, voffA);
;             PG8_WAIT_V(8); PG8_WAIT_L(0); PG8_BAR; PG8_MMA(0, 0, At, B0); PG8_MMA(0, 1, At, B1); PG8_BAR; PG8_SCHED;
;             PG8_LDA(At, 0, 1); PG8_STAGE(PG8_SB(0, 0), b2, voffB); PG8_STAGE(PG8_SB(0, 1), b2 + hstep, voffB); PG8_STAGE(PG8_SA(0, 0), a2, voffA);
.LBB0_496:
	s_add_u32 s26, s44, 0xfffc0080
	s_addc_u32 s27, s45, -1
	s_add_i32 s34, 0, 0x10000
	s_cmp_eq_u32 s33, 12
	s_cselect_b32 s49, s0, s27
	s_cselect_b32 s48, s1, s26
	v_add_u32_e32 v148, s34, v5
	s_cselect_b32 s47, s13, s19
	s_cselect_b32 s46, s15, s18
	s_add_i32 s26, 0, 0x14000
	ds_read_b128 v[144:147], v148
	ds_read_b128 v[174:177], v148 offset:1024
	ds_read_b128 v[178:181], v148 offset:2048
	ds_read_b128 v[182:185], v148 offset:3072
	v_add_u32_e32 v148, s26, v5
	ds_read_b128 v[186:189], v148
	ds_read_b128 v[190:193], v148 offset:1024
	ds_read_b128 v[194:197], v148 offset:2048
	ds_read_b128 v[198:201], v148 offset:3072
	v_lshl_add_u64 v[148:149], s[44:45], 0, v[140:141]
	s_add_i32 m0, s50, 0xc000
	ds_read_b128 v[202:205], v167
	ds_read_b128 v[206:209], v167 offset:1024
	ds_read_b128 v[210:213], v167 offset:2048
	ds_read_b128 v[218:221], v167 offset:3072
	ds_read_b128 v[222:225], v167 offset:4096
	ds_read_b128 v[226:229], v167 offset:5120
	ds_read_b128 v[230:233], v167 offset:6144
	ds_read_b128 v[234:237], v167 offset:7168
	global_load_lds_dwordx4 v[148:149], off
	v_lshl_add_u64 v[148:149], s[44:45], 0, v[142:143]
	s_add_i32 m0, s50, 0xe000
	s_nop 0
	global_load_lds_dwordx4 v[148:149], off
	s_waitcnt vmcnt(8)
	s_waitcnt lgkmcnt(0)
	s_barrier
	s_waitcnt lgkmcnt(0)
	v_mfma_f32_16x16x32_bf16 v[130:133], v[144:147], v[202:205], v[130:133]
	v_mfma_f32_16x16x32_bf16 v[126:129], v[178:181], v[202:205], v[126:129]
	v_mfma_f32_16x16x32_bf16 v[114:117], v[144:147], v[210:213], v[114:117]
	v_mfma_f32_16x16x32_bf16 v[110:113], v[178:181], v[210:213], v[110:113]
	v_mfma_f32_16x16x32_bf16 v[98:101], v[144:147], v[222:225], v[98:101]
	v_mfma_f32_16x16x32_bf16 v[94:97], v[178:181], v[222:225], v[94:97]
	v_mfma_f32_16x16x32_bf16 v[82:85], v[144:147], v[230:233], v[82:85]
	v_mfma_f32_16x16x32_bf16 v[78:81], v[178:181], v[230:233], v[78:81]
	v_mfma_f32_16x16x32_bf16 v[130:133], v[174:177], v[206:209], v[130:133]
	v_mfma_f32_16x16x32_bf16 v[126:129], v[182:185], v[206:209], v[126:129]
	v_mfma_f32_16x16x32_bf16 v[114:117], v[174:177], v[218:221], v[114:117]
	v_mfma_f32_16x16x32_bf16 v[110:113], v[182:185], v[218:221], v[110:113]
	v_mfma_f32_16x16x32_bf16 v[98:101], v[174:177], v[226:229], v[98:101]
	v_mfma_f32_16x16x32_bf16 v[94:97], v[182:185], v[226:229], v[94:97]
	v_mfma_f32_16x16x32_bf16 v[82:85], v[174:177], v[234:237], v[82:85]
	v_mfma_f32_16x16x32_bf16 v[78:81], v[182:185], v[234:237], v[78:81]
	v_mfma_f32_16x16x32_bf16 v[122:125], v[186:189], v[202:205], v[122:125]
	v_mfma_f32_16x16x32_bf16 v[118:121], v[194:197], v[202:205], v[118:121]
	v_mfma_f32_16x16x32_bf16 v[106:109], v[186:189], v[210:213], v[106:109]
	v_mfma_f32_16x16x32_bf16 v[102:105], v[194:197], v[210:213], v[102:105]
	v_mfma_f32_16x16x32_bf16 v[90:93], v[186:189], v[222:225], v[90:93]
	v_mfma_f32_16x16x32_bf16 v[86:89], v[194:197], v[222:225], v[86:89]
	v_mfma_f32_16x16x32_bf16 v[74:77], v[186:189], v[230:233], v[74:77]
	v_mfma_f32_16x16x32_bf16 v[70:73], v[194:197], v[230:233], v[70:73]
	v_mfma_f32_16x16x32_bf16 v[122:125], v[190:193], v[206:209], v[122:125]
	v_mfma_f32_16x16x32_bf16 v[118:121], v[198:201], v[206:209], v[118:121]
	v_mfma_f32_16x16x32_bf16 v[106:109], v[190:193], v[218:221], v[106:109]
	v_mfma_f32_16x16x32_bf16 v[102:105], v[198:201], v[218:221], v[102:105]
	v_mfma_f32_16x16x32_bf16 v[90:93], v[190:193], v[226:229], v[90:93]
	v_mfma_f32_16x16x32_bf16 v[86:89], v[198:201], v[226:229], v[86:89]
	v_mfma_f32_16x16x32_bf16 v[74:77], v[190:193], v[234:237], v[74:77]
	v_mfma_f32_16x16x32_bf16 v[70:73], v[198:201], v[234:237], v[70:73]
	s_barrier
	s_add_i32 s27, s34, s20
	v_lshl_add_u64 v[148:149], s[46:47], 0, v[134:135]
	s_mov_b32 m0, s27
	ds_read_b128 v[202:205], v167 offset:16384
	ds_read_b128 v[206:209], v167 offset:17408
	ds_read_b128 v[210:213], v167 offset:18432
	ds_read_b128 v[218:221], v167 offset:19456
	ds_read_b128 v[222:225], v167 offset:20480
	ds_read_b128 v[226:229], v167 offset:21504
	ds_read_b128 v[230:233], v167 offset:22528
	ds_read_b128 v[234:237], v167 offset:23552
	global_load_lds_dwordx4 v[148:149], off
	s_add_i32 m0, s27, 0x2000
	s_add_u32 s34, s46, 0x40000
	v_lshl_add_u64 v[160:161], s[46:47], 0, v[138:139]
	s_addc_u32 s35, s47, 0
	s_add_i32 s26, s26, s20
	global_load_lds_dwordx4 v[160:161], off
	v_lshl_add_u64 v[214:215], s[34:35], 0, v[134:135]
	s_mov_b32 m0, s26
	v_lshl_add_u64 v[238:239], s[48:49], 0, v[136:137]
	global_load_lds_dwordx4 v[214:215], off
	v_lshl_add_u64 v[214:215], s[34:35], 0, v[138:139]
	s_add_i32 m0, s26, 0x2000
	s_nop 0
	global_load_lds_dwordx4 v[214:215], off
	v_lshl_add_u64 v[214:215], s[48:49], 0, v[2:3]
	s_mov_b32 m0, s50
	s_nop 0
	global_load_lds_dwordx4 v[214:215], off
	s_mov_b32 m0, s51
	s_nop 0
	global_load_lds_dwordx4 v[238:239], off
	s_waitcnt vmcnt(8)
	s_waitcnt lgkmcnt(0)
	s_barrier
; #define PG8_STAGE(bufoff, gbase, voff) do { _Pragma("unroll") for (int _i = 0; _i < 2; ++_i) \
;         __builtin_amdgcn_global_load_lds((const unsigned*)((const char*)(gbase) + (voff)[_i]), (PG8_LAS unsigned*)(lds + (bufoff) + ldsw + _i * 8192), 16, 0, 0); } while (0)
; #define PG8_LDA(dst, b, h) do { _Pragma("unroll") for (int m = 0; m < 4; ++m) _Pragma("unroll") for (int k = 0; k < 2; ++k) dst[m][k] = *(const PG8_LAS bf16x8*)(lds + PG8_SA(b, h) + aoff + m * 2048 + k * 1024); } while (0)
; #define PG8_LDB(dst, b, h) do { _Pragma("unroll") for (int n = 0; n < 2; ++n) _Pragma("unroll") for (int k = 0; k < 2; ++k) dst[n][k] = *(const PG8_LAS bf16x8*)(lds + PG8_SB(b, h) + boff + n * 2048 + k * 1024); } while (0)
; #define PG8_MMA(ai, bj, At, Bt) do { __builtin_amdgcn_s_setprio(1); _Pragma("unroll") for (int m = 0; m < 4; ++m) _Pragma("unroll") for (int n = 0; n < 2; ++n) _Pragma("unroll") for (int k = 0; k < 2; ++k) \
;         acc[ai][bj][m][n] = __builtin_amdgcn_mfma_f32_16x16x32_bf16(Bt[n][k], At[m][k], acc[ai][bj][m][n], 0, 0, 0); __builtin_amdgcn_s_setprio(0); } while (0)
; #define PG8_WAIT_V(n) asm volatile("s_waitcnt vmcnt(" #n ")" ::: "memory")
; #define PG8_WAIT_L(n) asm volatile("s_waitcnt lgkmcnt(" #n ")" ::: "memory")
; #define PG8_BAR __builtin_amdgcn_s_barrier()
; #define PG8_SCHED __builtin_amdgcn_sched_barrier(0)
; template <class Epi, class Sched, bool ALIGN_EPI = false, bool SP2 = false>
; __device__ __forceinline__ void gemm_phase(PG8_LAS unsigned char* lds, const Gemm g, const Sched& S, const Epi& E, const int tid) {
;     ...
;             PG8_WAIT_V(8); PG8_WAIT_L(0); PG8_BAR; PG8_MMA(1, 0, At, B0); PG8_MMA(1, 1, At, B1); PG8_BAR; PG8_SCHED;
;             PG8_LDB(B0, 1, 0); PG8_LDB(B1, 1, 1); PG8_SCHED; PG8_LDA(At, 1, 0); PG8_STAGE(PG8_SA(0, 1), a2 + hstep, voffA);
;             PG8_WAIT_V(8); PG8_WAIT_L(0); PG8_BAR; PG8_MMA(0, 0, At, B0); PG8_MMA(0, 1, At, B1); PG8_BAR; PG8_SCHED;
	s_waitcnt lgkmcnt(0)
	v_mfma_f32_16x16x32_bf16 v[66:69], v[144:147], v[202:205], v[66:69]
	v_mfma_f32_16x16x32_bf16 v[62:65], v[178:181], v[202:205], v[62:65]
	v_mfma_f32_16x16x32_bf16 v[50:53], v[144:147], v[210:213], v[50:53]
	v_mfma_f32_16x16x32_bf16 v[46:49], v[178:181], v[210:213], v[46:49]
	v_mfma_f32_16x16x32_bf16 v[34:37], v[144:147], v[222:225], v[34:37]
	v_mfma_f32_16x16x32_bf16 v[30:33], v[178:181], v[222:225], v[30:33]
	v_mfma_f32_16x16x32_bf16 v[18:21], v[144:147], v[230:233], v[18:21]
	v_mfma_f32_16x16x32_bf16 v[14:17], v[178:181], v[230:233], v[14:17]
	v_mfma_f32_16x16x32_bf16 v[66:69], v[174:177], v[206:209], v[66:69]
	v_mfma_f32_16x16x32_bf16 v[62:65], v[182:185], v[206:209], v[62:65]
	v_mfma_f32_16x16x32_bf16 v[50:53], v[174:177], v[218:221], v[50:53]
	v_mfma_f32_16x16x32_bf16 v[46:49], v[182:185], v[218:221], v[46:49]
	v_mfma_f32_16x16x32_bf16 v[34:37], v[174:177], v[226:229], v[34:37]
	v_mfma_f32_16x16x32_bf16 v[30:33], v[182:185], v[226:229], v[30:33]
	v_mfma_f32_16x16x32_bf16 v[18:21], v[174:177], v[234:237], v[18:21]
	v_mfma_f32_16x16x32_bf16 v[14:17], v[182:185], v[234:237], v[14:17]
	v_mfma_f32_16x16x32_bf16 v[58:61], v[186:189], v[202:205], v[58:61]
	v_mfma_f32_16x16x32_bf16 v[54:57], v[194:197], v[202:205], v[54:57]
	v_mfma_f32_16x16x32_bf16 v[42:45], v[186:189], v[210:213], v[42:45]
	v_mfma_f32_16x16x32_bf16 v[38:41], v[194:197], v[210:213], v[38:41]
	v_mfma_f32_16x16x32_bf16 v[26:29], v[186:189], v[222:225], v[26:29]
	v_mfma_f32_16x16x32_bf16 v[22:25], v[194:197], v[222:225], v[22:25]
	v_mfma_f32_16x16x32_bf16 v[10:13], v[186:189], v[230:233], v[10:13]
	v_mfma_f32_16x16x32_bf16 v[6:9], v[194:197], v[230:233], v[6:9]
	v_mfma_f32_16x16x32_bf16 v[58:61], v[190:193], v[206:209], v[58:61]
	v_mfma_f32_16x16x32_bf16 v[54:57], v[198:201], v[206:209], v[54:57]
	v_mfma_f32_16x16x32_bf16 v[42:45], v[190:193], v[218:221], v[42:45]
	v_mfma_f32_16x16x32_bf16 v[38:41], v[198:201], v[218:221], v[38:41]
	v_mfma_f32_16x16x32_bf16 v[26:29], v[190:193], v[226:229], v[26:29]
	v_mfma_f32_16x16x32_bf16 v[22:25], v[198:201], v[226:229], v[22:25]
	v_mfma_f32_16x16x32_bf16 v[10:13], v[190:193], v[234:237], v[10:13]
	v_mfma_f32_16x16x32_bf16 v[6:9], v[198:201], v[234:237], v[6:9]
	s_barrier
	s_add_i32 s26, 0, 0x18000
	s_add_i32 s27, 0, 0x1c000
	v_add_u32_e32 v182, s26, v5
	v_add_u32_e32 v198, s27, v5
	ds_read_b128 v[144:147], v182
	ds_read_b128 v[174:177], v182 offset:1024
	ds_read_b128 v[178:181], v182 offset:2048
	ds_read_b128 v[182:185], v182 offset:3072
	ds_read_b128 v[186:189], v198
	ds_read_b128 v[190:193], v198 offset:1024
	ds_read_b128 v[194:197], v198 offset:2048
	ds_read_b128 v[198:201], v198 offset:3072
	s_add_u32 s34, s48, 0x40000
	s_addc_u32 s35, s49, 0
	s_mov_b32 m0, s52
	v_lshl_add_u64 v[240:241], s[34:35], 0, v[2:3]
	ds_read_b128 v[202:205], v167 offset:32768
	ds_read_b128 v[206:209], v167 offset:33792
	ds_read_b128 v[210:213], v167 offset:34816
	ds_read_b128 v[218:221], v167 offset:35840
	ds_read_b128 v[222:225], v167 offset:36864
	ds_read_b128 v[226:229], v167 offset:37888
	ds_read_b128 v[230:233], v167 offset:38912
	ds_read_b128 v[234:237], v167 offset:39936
	global_load_lds_dwordx4 v[240:241], off
	v_lshl_add_u64 v[240:241], s[34:35], 0, v[136:137]
	s_mov_b32 m0, s53
	s_nop 0
	global_load_lds_dwordx4 v[240:241], off
	s_waitcnt vmcnt(8)
	s_waitcnt lgkmcnt(0)
	s_barrier
	s_waitcnt lgkmcnt(0)
	v_mfma_f32_16x16x32_bf16 v[130:133], v[144:147], v[202:205], v[130:133]
	v_mfma_f32_16x16x32_bf16 v[126:129], v[178:181], v[202:205], v[126:129]
	v_mfma_f32_16x16x32_bf16 v[114:117], v[144:147], v[210:213], v[114:117]
	v_mfma_f32_16x16x32_bf16 v[110:113], v[178:181], v[210:213], v[110:113]
	v_mfma_f32_16x16x32_bf16 v[98:101], v[144:147], v[222:225], v[98:101]
	v_mfma_f32_16x16x32_bf16 v[94:97], v[178:181], v[222:225], v[94:97]
	v_mfma_f32_16x16x32_bf16 v[82:85], v[144:147], v[230:233], v[82:85]
	v_mfma_f32_16x16x32_bf16 v[78:81], v[178:181], v[230:233], v[78:81]
	v_mfma_f32_16x16x32_bf16 v[130:133], v[174:177], v[206:209], v[130:133]
	v_mfma_f32_16x16x32_bf16 v[126:129], v[182:185], v[206:209], v[126:129]
	v_mfma_f32_16x16x32_bf16 v[114:117], v[174:177], v[218:221], v[114:117]
	v_mfma_f32_16x16x32_bf16 v[110:113], v[182:185], v[218:221], v[110:113]
	v_mfma_f32_16x16x32_bf16 v[98:101], v[174:177], v[226:229], v[98:101]
	v_mfma_f32_16x16x32_bf16 v[94:97], v[182:185], v[226:229], v[94:97]
	v_mfma_f32_16x16x32_bf16 v[82:85], v[174:177], v[234:237], v[82:85]
	v_mfma_f32_16x16x32_bf16 v[78:81], v[182:185], v[234:237], v[78:81]
	v_mfma_f32_16x16x32_bf16 v[122:125], v[186:189], v[202:205], v[122:125]
	v_mfma_f32_16x16x32_bf16 v[118:121], v[194:197], v[202:205], v[118:121]
	v_mfma_f32_16x16x32_bf16 v[106:109], v[186:189], v[210:213], v[106:109]
	v_mfma_f32_16x16x32_bf16 v[102:105], v[194:197], v[210:213], v[102:105]
	v_mfma_f32_16x16x32_bf16 v[90:93], v[186:189], v[222:225], v[90:93]
	v_mfma_f32_16x16x32_bf16 v[86:89], v[194:197], v[222:225], v[86:89]
	v_mfma_f32_16x16x32_bf16 v[74:77], v[186:189], v[230:233], v[74:77]
	v_mfma_f32_16x16x32_bf16 v[70:73], v[194:197], v[230:233], v[70:73]
	v_mfma_f32_16x16x32_bf16 v[122:125], v[190:193], v[206:209], v[122:125]
	v_mfma_f32_16x16x32_bf16 v[118:121], v[198:201], v[206:209], v[118:121]
	v_mfma_f32_16x16x32_bf16 v[106:109], v[190:193], v[218:221], v[106:109]
	v_mfma_f32_16x16x32_bf16 v[102:105], v[198:201], v[218:221], v[102:105]
	v_mfma_f32_16x16x32_bf16 v[90:93], v[190:193], v[226:229], v[90:93]
	v_mfma_f32_16x16x32_bf16 v[86:89], v[198:201], v[226:229], v[86:89]
	v_mfma_f32_16x16x32_bf16 v[74:77], v[190:193], v[234:237], v[74:77]
	v_mfma_f32_16x16x32_bf16 v[70:73], v[198:201], v[234:237], v[70:73]
	s_barrier
; #define PG8_STAGE(bufoff, gbase, voff) do { _Pragma("unroll") for (int _i = 0; _i < 2; ++_i) \
;         __builtin_amdgcn_global_load_lds((const unsigned*)((const char*)(gbase) + (voff)[_i]), (PG8_LAS unsigned*)(lds + (bufoff) + ldsw + _i * 8192), 16, 0, 0); } while (0)
; #define PG8_LDA(dst, b, h) do { _Pragma("unroll") for (int m = 0; m < 4; ++m) _Pragma("unroll") for (int k = 0; k < 2; ++k) dst[m][k] = *(const PG8_LAS bf16x8*)(lds + PG8_SA(b, h) + aoff + m * 2048 + k * 1024); } while (0)
; #define PG8_MMA(ai, bj, At, Bt) do { __builtin_amdgcn_s_setprio(1); _Pragma("unroll") for (int m = 0; m < 4; ++m) _Pragma("unroll") for (int n = 0; n < 2; ++n) _Pragma("unroll") for (int k = 0; k < 2; ++k) \
;         acc[ai][bj][m][n] = __builtin_amdgcn_mfma_f32_16x16x32_bf16(Bt[n][k], At[m][k], acc[ai][bj][m][n], 0, 0, 0); __builtin_amdgcn_s_setprio(0); } while (0)
; #define PG8_WAIT_V(n) asm volatile("s_waitcnt vmcnt(" #n ")" ::: "memory")
; #define PG8_WAIT_L(n) asm volatile("s_waitcnt lgkmcnt(" #n ")" ::: "memory")
; #define PG8_BAR __builtin_amdgcn_s_barrier()
; #define PG8_SCHED __builtin_amdgcn_sched_barrier(0)
; template <class Epi, class Sched, bool ALIGN_EPI = false, bool SP2 = false>
; __device__ __forceinline__ void gemm_phase(PG8_LAS unsigned char* lds, const Gemm g, const Sched& S, const Epi& E, const int tid) {
;     ...
;             PG8_LDA(At, 1, 1); PG8_STAGE(PG8_SB(1, 0), b3, voffB); PG8_STAGE(PG8_SB(1, 1), b3 + hstep, voffB); PG8_STAGE(PG8_SA(1, 0), a3, voffA);
;             PG8_WAIT_V(8); PG8_WAIT_L(0); PG8_BAR; PG8_MMA(1, 0, At, B0); PG8_MMA(1, 1, At, B1); PG8_BAR; PG8_SCHED;
;     ...
;         if constexpr (ALIGN_EPI) { if (wr == 0) PG8_BAR; }
	s_add_i32 s26, s26, s20
	v_lshl_add_u64 v[148:149], v[148:149], 0, s[16:17]
	s_mov_b32 m0, s26
	ds_read_b128 v[202:205], v167 offset:49152
	ds_read_b128 v[206:209], v167 offset:50176
	ds_read_b128 v[210:213], v167 offset:51200
	ds_read_b128 v[218:221], v167 offset:52224
	ds_read_b128 v[222:225], v167 offset:53248
	ds_read_b128 v[226:229], v167 offset:54272
	ds_read_b128 v[230:233], v167 offset:55296
	ds_read_b128 v[234:237], v167 offset:56320
	global_load_lds_dwordx4 v[148:149], off
	s_add_i32 m0, s26, 0x2000
	s_add_u32 s34, s46, 0x40080
	v_lshl_add_u64 v[148:149], v[160:161], 0, s[16:17]
	s_addc_u32 s35, s47, 0
	s_add_i32 s26, s27, s20
	global_load_lds_dwordx4 v[148:149], off
	v_lshl_add_u64 v[148:149], s[34:35], 0, v[134:135]
	s_mov_b32 m0, s26
	s_nop 0
	global_load_lds_dwordx4 v[148:149], off
	v_lshl_add_u64 v[148:149], s[34:35], 0, v[138:139]
	s_add_i32 m0, s26, 0x2000
	s_nop 0
	global_load_lds_dwordx4 v[148:149], off
	v_lshl_add_u64 v[148:149], v[214:215], 0, s[16:17]
	s_mov_b32 m0, s54
	s_nop 0
	global_load_lds_dwordx4 v[148:149], off
	v_lshl_add_u64 v[148:149], v[238:239], 0, s[16:17]
	s_mov_b32 m0, s55
	s_nop 0
	global_load_lds_dwordx4 v[148:149], off
	s_waitcnt vmcnt(8)
	s_waitcnt lgkmcnt(0)
	s_barrier
	s_waitcnt lgkmcnt(0)
	v_mfma_f32_16x16x32_bf16 v[66:69], v[144:147], v[202:205], v[66:69]
	v_mfma_f32_16x16x32_bf16 v[62:65], v[178:181], v[202:205], v[62:65]
	v_mfma_f32_16x16x32_bf16 v[50:53], v[144:147], v[210:213], v[50:53]
	v_mfma_f32_16x16x32_bf16 v[46:49], v[178:181], v[210:213], v[46:49]
	v_mfma_f32_16x16x32_bf16 v[34:37], v[144:147], v[222:225], v[34:37]
	v_mfma_f32_16x16x32_bf16 v[30:33], v[178:181], v[222:225], v[30:33]
	v_mfma_f32_16x16x32_bf16 v[18:21], v[144:147], v[230:233], v[18:21]
	v_mfma_f32_16x16x32_bf16 v[14:17], v[178:181], v[230:233], v[14:17]
	v_mfma_f32_16x16x32_bf16 v[66:69], v[174:177], v[206:209], v[66:69]
	v_mfma_f32_16x16x32_bf16 v[62:65], v[182:185], v[206:209], v[62:65]
	v_mfma_f32_16x16x32_bf16 v[50:53], v[174:177], v[218:221], v[50:53]
	v_mfma_f32_16x16x32_bf16 v[46:49], v[182:185], v[218:221], v[46:49]
	v_mfma_f32_16x16x32_bf16 v[34:37], v[174:177], v[226:229], v[34:37]
	v_mfma_f32_16x16x32_bf16 v[30:33], v[182:185], v[226:229], v[30:33]
	v_mfma_f32_16x16x32_bf16 v[18:21], v[174:177], v[234:237], v[18:21]
	v_mfma_f32_16x16x32_bf16 v[14:17], v[182:185], v[234:237], v[14:17]
	v_mfma_f32_16x16x32_bf16 v[58:61], v[186:189], v[202:205], v[58:61]
	v_mfma_f32_16x16x32_bf16 v[54:57], v[194:197], v[202:205], v[54:57]
	v_mfma_f32_16x16x32_bf16 v[42:45], v[186:189], v[210:213], v[42:45]
	v_mfma_f32_16x16x32_bf16 v[38:41], v[194:197], v[210:213], v[38:41]
	v_mfma_f32_16x16x32_bf16 v[26:29], v[186:189], v[222:225], v[26:29]
	v_mfma_f32_16x16x32_bf16 v[22:25], v[194:197], v[222:225], v[22:25]
	v_mfma_f32_16x16x32_bf16 v[10:13], v[186:189], v[230:233], v[10:13]
	v_mfma_f32_16x16x32_bf16 v[6:9], v[194:197], v[230:233], v[6:9]
	v_mfma_f32_16x16x32_bf16 v[58:61], v[190:193], v[206:209], v[58:61]
	v_mfma_f32_16x16x32_bf16 v[54:57], v[198:201], v[206:209], v[54:57]
	v_mfma_f32_16x16x32_bf16 v[42:45], v[190:193], v[218:221], v[42:45]
	v_mfma_f32_16x16x32_bf16 v[38:41], v[198:201], v[218:221], v[38:41]
	v_mfma_f32_16x16x32_bf16 v[26:29], v[190:193], v[226:229], v[26:29]
	v_mfma_f32_16x16x32_bf16 v[22:25], v[198:201], v[226:229], v[22:25]
	v_mfma_f32_16x16x32_bf16 v[10:13], v[190:193], v[234:237], v[10:13]
	v_mfma_f32_16x16x32_bf16 v[6:9], v[198:201], v[234:237], v[6:9]
	s_add_i32 s33, s33, 2
	s_add_u32 s44, s44, 0x100
	s_addc_u32 s45, s45, 0
	s_add_u32 s18, s18, 0x100
	s_addc_u32 s19, s19, 0
	s_cmp_gt_u32 s33, 13
	s_barrier
	s_cbranch_scc0 .LBB0_496
	s_and_b64 vcc, exec, s[10:11]
	s_cbranch_vccz .LBB0_499
	s_barrier

; #define PG8_STAGE(bufoff, gbase, voff) do { _Pragma("unroll") for (int _i = 0; _i < 2; ++_i) \
;         __builtin_amdgcn_global_load_lds((const unsigned*)((const char*)(gbase) + (voff)[_i]), (PG8_LAS unsigned*)(lds + (bufoff) + ldsw + _i * 8192), 16, 0, 0); } while (0)
; #define PG8_LDA(dst, b, h) do { _Pragma("unroll") for (int m = 0; m < 4; ++m) _Pragma("unroll") for (int k = 0; k < 2; ++k) dst[m][k] = *(const PG8_LAS bf16x8*)(lds + PG8_SA(b, h) + aoff + m * 2048 + k * 1024); } while (0)
; #define PG8_LDB(dst, b, h) do { _Pragma("unroll") for (int n = 0; n < 2; ++n) _Pragma("unroll") for (int k = 0; k < 2; ++k) dst[n][k] = *(const PG8_LAS bf16x8*)(lds + PG8_SB(b, h) + boff + n * 2048 + k * 1024); } while (0)
; #define PG8_MMA(ai, bj, At, Bt) do { __builtin_amdgcn_s_setprio(1); _Pragma("unroll") for (int m = 0; m < 4; ++m) _Pragma("unroll") for (int n = 0; n < 2; ++n) _Pragma("unroll") for (int k = 0; k < 2; ++k) \
;         acc[ai][bj][m][n] = __builtin_amdgcn_mfma_f32_16x16x32_bf16(Bt[n][k], At[m][k], acc[ai][bj][m][n], 0, 0, 0); __builtin_amdgcn_s_setprio(0); } while (0)
; #define PG8_WAIT_V(n) asm volatile("s_waitcnt vmcnt(" #n ")" ::: "memory")
; #define PG8_WAIT_L(n) asm volatile("s_waitcnt lgkmcnt(" #n ")" ::: "memory")
; #define PG8_BAR __builtin_amdgcn_s_barrier()
; #define PG8_SCHED __builtin_amdgcn_sched_barrier(0)
; template <class Epi, class Sched, bool ALIGN_EPI = false, bool SP2 = false>
; __device__ __forceinline__ void gemm_phase(PG8_LAS unsigned char* lds, const Gemm g, const Sched& S, const Epi& E, const int tid) {
;     ...
;             const bool last = (t == nt - 2);
;             const char* a1 = cA + (size_t)(t + 1) * kstep;
;             const char* a2 = last ? nA : cA + (size_t)(t + 2) * kstep; const char* b2 = last ? nB : cB + (size_t)(t + 2) * kstep;
;             const char* a3 = a2 + kstep; const char* b3 = b2 + kstep;
;             if (last && has_next) S.a_ready(nxt);
;             if constexpr (SP2) {
;             PG8_LDB(B0, 0, 0); PG8_LDB(B1, 0, 1); PG8_SCHED; PG8_LDA(At, 0, 0); PG8_STAGE(PG8_SA(1, 1), a1 + hstep, voffA);
;             PG8_WAIT_V(8); PG8_WAIT_L(0); PG8_BAR; PG8_MMA(0, 0, At, B0); PG8_MMA(0, 1, At, B1); PG8_BAR; PG8_SCHED;
;             PG8_LDA(At, 0, 1); PG8_STAGE(PG8_SB(0, 0), b2, voffB); PG8_STAGE(PG8_SB(0, 1), b2 + hstep, voffB); PG8_STAGE(PG8_SA(0, 0), a2, voffA);
.LBB0_641:
	s_add_u32 s26, s44, 0xfffc0080
	s_addc_u32 s27, s45, -1
	s_add_i32 s35, 0, 0x10000
	s_cmp_eq_u32 s34, 12
	s_cselect_b32 s63, s57, s27
	s_cselect_b32 s62, s56, s26
	s_cselect_b32 s61, s1, s33
	s_cselect_b32 s60, s18, s19
	s_add_i32 s26, 0, 0x14000
	v_add_u32_e32 v58, s35, v159
	v_add_u32_e32 v160, s26, v159
	ds_read_b128 v[46:49], v58
	ds_read_b128 v[50:53], v58 offset:1024
	ds_read_b128 v[54:57], v58 offset:2048
	ds_read_b128 v[58:61], v58 offset:3072
	ds_read_b128 v[70:73], v160
	ds_read_b128 v[74:77], v160 offset:1024
	ds_read_b128 v[174:177], v160 offset:2048
	ds_read_b128 v[178:181], v160 offset:3072
	v_lshl_add_u64 v[160:161], s[44:45], 0, v[170:171]
	s_add_i32 m0, s68, 0xc000
	ds_read_b128 v[182:185], v243
	ds_read_b128 v[186:189], v243 offset:1024
	ds_read_b128 v[190:193], v243 offset:2048
	ds_read_b128 v[194:197], v243 offset:3072
	ds_read_b128 v[198:201], v243 offset:4096
	ds_read_b128 v[202:205], v243 offset:5120
	ds_read_b128 v[206:209], v243 offset:6144
	ds_read_b128 v[210:213], v243 offset:7168
	global_load_lds_dwordx4 v[160:161], off
	v_lshl_add_u64 v[160:161], s[44:45], 0, v[172:173]
	s_add_i32 m0, s68, 0xe000
	s_nop 0
	global_load_lds_dwordx4 v[160:161], off
	s_waitcnt vmcnt(8)
	s_waitcnt lgkmcnt(0)
	s_barrier
	s_waitcnt lgkmcnt(0)
	v_mfma_f32_16x16x32_bf16 v[62:65], v[46:49], v[182:185], v[62:65]
	v_mfma_f32_16x16x32_bf16 v[146:149], v[54:57], v[182:185], v[146:149]
	v_mfma_f32_16x16x32_bf16 v[66:69], v[46:49], v[190:193], v[66:69]
	v_mfma_f32_16x16x32_bf16 v[154:157], v[54:57], v[190:193], v[154:157]
	v_mfma_f32_16x16x32_bf16 v[138:141], v[46:49], v[198:201], v[138:141]
	v_mfma_f32_16x16x32_bf16 v[134:137], v[54:57], v[198:201], v[134:137]
	v_mfma_f32_16x16x32_bf16 v[122:125], v[46:49], v[206:209], v[122:125]
	v_mfma_f32_16x16x32_bf16 v[118:121], v[54:57], v[206:209], v[118:121]
	v_mfma_f32_16x16x32_bf16 v[62:65], v[50:53], v[186:189], v[62:65]
	v_mfma_f32_16x16x32_bf16 v[146:149], v[58:61], v[186:189], v[146:149]
	v_mfma_f32_16x16x32_bf16 v[66:69], v[50:53], v[194:197], v[66:69]
	v_mfma_f32_16x16x32_bf16 v[154:157], v[58:61], v[194:197], v[154:157]
	v_mfma_f32_16x16x32_bf16 v[138:141], v[50:53], v[202:205], v[138:141]
	v_mfma_f32_16x16x32_bf16 v[134:137], v[58:61], v[202:205], v[134:137]
	v_mfma_f32_16x16x32_bf16 v[122:125], v[50:53], v[210:213], v[122:125]
	v_mfma_f32_16x16x32_bf16 v[118:121], v[58:61], v[210:213], v[118:121]
	v_mfma_f32_16x16x32_bf16 v[150:153], v[70:73], v[182:185], v[150:153]
	v_mfma_f32_16x16x32_bf16 v[142:145], v[174:177], v[182:185], v[142:145]
	v_mfma_f32_16x16x32_bf16 v[130:133], v[70:73], v[190:193], v[130:133]
	v_mfma_f32_16x16x32_bf16 v[126:129], v[174:177], v[190:193], v[126:129]
	v_mfma_f32_16x16x32_bf16 v[114:117], v[70:73], v[198:201], v[114:117]
	v_mfma_f32_16x16x32_bf16 v[110:113], v[174:177], v[198:201], v[110:113]
	v_mfma_f32_16x16x32_bf16 v[106:109], v[70:73], v[206:209], v[106:109]
	v_mfma_f32_16x16x32_bf16 v[102:105], v[174:177], v[206:209], v[102:105]
	v_mfma_f32_16x16x32_bf16 v[150:153], v[74:77], v[186:189], v[150:153]
	v_mfma_f32_16x16x32_bf16 v[142:145], v[178:181], v[186:189], v[142:145]
	v_mfma_f32_16x16x32_bf16 v[130:133], v[74:77], v[194:197], v[130:133]
	v_mfma_f32_16x16x32_bf16 v[126:129], v[178:181], v[194:197], v[126:129]
	v_mfma_f32_16x16x32_bf16 v[114:117], v[74:77], v[202:205], v[114:117]
	v_mfma_f32_16x16x32_bf16 v[110:113], v[178:181], v[202:205], v[110:113]
	v_mfma_f32_16x16x32_bf16 v[106:109], v[74:77], v[210:213], v[106:109]
	v_mfma_f32_16x16x32_bf16 v[102:105], v[178:181], v[210:213], v[102:105]
	s_barrier
	s_add_i32 s27, s35, s67
	v_lshl_add_u64 v[160:161], s[60:61], 0, v[164:165]
	s_mov_b32 m0, s27
	ds_read_b128 v[182:185], v243 offset:16384
	ds_read_b128 v[186:189], v243 offset:17408
	ds_read_b128 v[190:193], v243 offset:18432
	ds_read_b128 v[194:197], v243 offset:19456
	ds_read_b128 v[198:201], v243 offset:20480
	ds_read_b128 v[202:205], v243 offset:21504
	ds_read_b128 v[206:209], v243 offset:22528
	ds_read_b128 v[210:213], v243 offset:23552
	global_load_lds_dwordx4 v[160:161], off
	s_add_i32 m0, s27, 0x2000
	s_add_u32 s64, s60, 0x40000
	v_lshl_add_u64 v[214:215], s[60:61], 0, v[168:169]
	s_addc_u32 s65, s61, 0
	s_add_i32 s26, s26, s67
	global_load_lds_dwordx4 v[214:215], off
	v_lshl_add_u64 v[244:245], s[64:65], 0, v[164:165]
	s_mov_b32 m0, s26
	v_lshl_add_u64 v[248:249], s[62:63], 0, v[2:3]
	global_load_lds_dwordx4 v[244:245], off
	v_lshl_add_u64 v[244:245], s[64:65], 0, v[168:169]
	s_add_i32 m0, s26, 0x2000
	v_lshl_add_u64 v[250:251], s[62:63], 0, v[166:167]
	global_load_lds_dwordx4 v[244:245], off
	s_mov_b32 m0, s68
	s_nop 0
	global_load_lds_dwordx4 v[248:249], off
	s_mov_b32 m0, s69
	s_nop 0
	global_load_lds_dwordx4 v[250:251], off
	s_waitcnt vmcnt(8)
	s_waitcnt lgkmcnt(0)
	s_barrier
; #define PG8_STAGE(bufoff, gbase, voff) do { _Pragma("unroll") for (int _i = 0; _i < 2; ++_i) \
;         __builtin_amdgcn_global_load_lds((const unsigned*)((const char*)(gbase) + (voff)[_i]), (PG8_LAS unsigned*)(lds + (bufoff) + ldsw + _i * 8192), 16, 0, 0); } while (0)
; #define PG8_LDA(dst, b, h) do { _Pragma("unroll") for (int m = 0; m < 4; ++m) _Pragma("unroll") for (int k = 0; k < 2; ++k) dst[m][k] = *(const PG8_LAS bf16x8*)(lds + PG8_SA(b, h) + aoff + m * 2048 + k * 1024); } while (0)
; #define PG8_LDB(dst, b, h) do { _Pragma("unroll") for (int n = 0; n < 2; ++n) _Pragma("unroll") for (int k = 0; k < 2; ++k) dst[n][k] = *(const PG8_LAS bf16x8*)(lds + PG8_SB(b, h) + boff + n * 2048 + k * 1024); } while (0)
; #define PG8_MMA(ai, bj, At, Bt) do { __builtin_amdgcn_s_setprio(1); _Pragma("unroll") for (int m = 0; m < 4; ++m) _Pragma("unroll") for (int n = 0; n < 2; ++n) _Pragma("unroll") for (int k = 0; k < 2; ++k) \
;         acc[ai][bj][m][n] = __builtin_amdgcn_mfma_f32_16x16x32_bf16(Bt[n][k], At[m][k], acc[ai][bj][m][n], 0, 0, 0); __builtin_amdgcn_s_setprio(0); } while (0)
; #define PG8_WAIT_V(n) asm volatile("s_waitcnt vmcnt(" #n ")" ::: "memory")
; #define PG8_WAIT_L(n) asm volatile("s_waitcnt lgkmcnt(" #n ")" ::: "memory")
; #define PG8_BAR __builtin_amdgcn_s_barrier()
; #define PG8_SCHED __builtin_amdgcn_sched_barrier(0)
; template <class Epi, class Sched, bool ALIGN_EPI = false, bool SP2 = false>
; __device__ __forceinline__ void gemm_phase(PG8_LAS unsigned char* lds, const Gemm g, const Sched& S, const Epi& E, const int tid) {
;     ...
;             PG8_WAIT_V(8); PG8_WAIT_L(0); PG8_BAR; PG8_MMA(1, 0, At, B0); PG8_MMA(1, 1, At, B1); PG8_BAR; PG8_SCHED;
;             PG8_LDB(B0, 1, 0); PG8_LDB(B1, 1, 1); PG8_SCHED; PG8_LDA(At, 1, 0); PG8_STAGE(PG8_SA(0, 1), a2 + hstep, voffA);
;             PG8_WAIT_V(8); PG8_WAIT_L(0); PG8_BAR; PG8_MMA(0, 0, At, B0); PG8_MMA(0, 1, At, B1); PG8_BAR; PG8_SCHED;
	s_waitcnt lgkmcnt(0)
	v_mfma_f32_16x16x32_bf16 v[90:93], v[46:49], v[182:185], v[90:93]
	v_mfma_f32_16x16x32_bf16 v[86:89], v[54:57], v[182:185], v[86:89]
	v_mfma_f32_16x16x32_bf16 v[98:101], v[46:49], v[190:193], v[98:101]
	v_mfma_f32_16x16x32_bf16 v[94:97], v[54:57], v[190:193], v[94:97]
	v_mfma_f32_16x16x32_bf16 v[42:45], v[46:49], v[198:201], v[42:45]
	v_mfma_f32_16x16x32_bf16 v[38:41], v[54:57], v[198:201], v[38:41]
	v_mfma_f32_16x16x32_bf16 v[26:29], v[46:49], v[206:209], v[26:29]
	v_mfma_f32_16x16x32_bf16 v[22:25], v[54:57], v[206:209], v[22:25]
	v_mfma_f32_16x16x32_bf16 v[90:93], v[50:53], v[186:189], v[90:93]
	v_mfma_f32_16x16x32_bf16 v[86:89], v[58:61], v[186:189], v[86:89]
	v_mfma_f32_16x16x32_bf16 v[98:101], v[50:53], v[194:197], v[98:101]
	v_mfma_f32_16x16x32_bf16 v[94:97], v[58:61], v[194:197], v[94:97]
	v_mfma_f32_16x16x32_bf16 v[42:45], v[50:53], v[202:205], v[42:45]
	v_mfma_f32_16x16x32_bf16 v[38:41], v[58:61], v[202:205], v[38:41]
	v_mfma_f32_16x16x32_bf16 v[26:29], v[50:53], v[210:213], v[26:29]
	v_mfma_f32_16x16x32_bf16 v[22:25], v[58:61], v[210:213], v[22:25]
	v_mfma_f32_16x16x32_bf16 v[34:37], v[70:73], v[190:193], v[34:37]
	v_mfma_f32_16x16x32_bf16 v[30:33], v[174:177], v[190:193], v[30:33]
	v_mfma_f32_16x16x32_bf16 v[18:21], v[70:73], v[198:201], v[18:21]
	v_mfma_f32_16x16x32_bf16 v[14:17], v[174:177], v[198:201], v[14:17]
	v_mfma_f32_16x16x32_bf16 v[10:13], v[70:73], v[206:209], v[10:13]
	v_mfma_f32_16x16x32_bf16 v[6:9], v[174:177], v[206:209], v[6:9]
	v_mfma_f32_16x16x32_bf16 v[46:49], v[70:73], v[182:185], v[82:85]
	v_mfma_f32_16x16x32_bf16 v[50:53], v[174:177], v[182:185], v[78:81]
	v_mfma_f32_16x16x32_bf16 v[34:37], v[74:77], v[194:197], v[34:37]
	v_mfma_f32_16x16x32_bf16 v[30:33], v[178:181], v[194:197], v[30:33]
	v_mfma_f32_16x16x32_bf16 v[18:21], v[74:77], v[202:205], v[18:21]
	v_mfma_f32_16x16x32_bf16 v[14:17], v[178:181], v[202:205], v[14:17]
	v_mfma_f32_16x16x32_bf16 v[10:13], v[74:77], v[210:213], v[10:13]
	v_mfma_f32_16x16x32_bf16 v[6:9], v[178:181], v[210:213], v[6:9]
	v_mfma_f32_16x16x32_bf16 v[46:49], v[74:77], v[186:189], v[46:49]
	v_mfma_f32_16x16x32_bf16 v[50:53], v[178:181], v[186:189], v[50:53]
	s_barrier
	s_add_i32 s26, 0, 0x18000
	s_add_i32 s27, 0, 0x1c000
	v_add_u32_e32 v74, s26, v159
	v_add_u32_e32 v78, s27, v159
	ds_read_b128 v[54:57], v74
	ds_read_b128 v[58:61], v74 offset:1024
	ds_read_b128 v[70:73], v74 offset:2048
	ds_read_b128 v[74:77], v74 offset:3072
	ds_read_b128 v[174:177], v78
	ds_read_b128 v[178:181], v78 offset:1024
	ds_read_b128 v[182:185], v78 offset:2048
	ds_read_b128 v[186:189], v78 offset:3072
	s_add_u32 s62, s62, 0x40000
	s_addc_u32 s63, s63, 0
	s_mov_b32 m0, s70
	v_lshl_add_u64 v[244:245], s[62:63], 0, v[2:3]
	ds_read_b128 v[78:81], v243 offset:32768
	ds_read_b128 v[82:85], v243 offset:33792
	ds_read_b128 v[190:193], v243 offset:34816
	ds_read_b128 v[194:197], v243 offset:35840
	ds_read_b128 v[198:201], v243 offset:36864
	ds_read_b128 v[202:205], v243 offset:37888
	ds_read_b128 v[206:209], v243 offset:38912
	ds_read_b128 v[210:213], v243 offset:39936
	global_load_lds_dwordx4 v[244:245], off
	v_lshl_add_u64 v[244:245], s[62:63], 0, v[166:167]
	s_mov_b32 m0, s71
	s_nop 0
	global_load_lds_dwordx4 v[244:245], off
	s_waitcnt vmcnt(8)
	s_waitcnt lgkmcnt(0)
	s_barrier
	s_waitcnt lgkmcnt(0)
	v_mfma_f32_16x16x32_bf16 v[62:65], v[54:57], v[78:81], v[62:65]
	v_mfma_f32_16x16x32_bf16 v[146:149], v[70:73], v[78:81], v[146:149]
	v_mfma_f32_16x16x32_bf16 v[66:69], v[54:57], v[190:193], v[66:69]
	v_mfma_f32_16x16x32_bf16 v[154:157], v[70:73], v[190:193], v[154:157]
	v_mfma_f32_16x16x32_bf16 v[138:141], v[54:57], v[198:201], v[138:141]
	v_mfma_f32_16x16x32_bf16 v[134:137], v[70:73], v[198:201], v[134:137]
	v_mfma_f32_16x16x32_bf16 v[122:125], v[54:57], v[206:209], v[122:125]
	v_mfma_f32_16x16x32_bf16 v[118:121], v[70:73], v[206:209], v[118:121]
	v_mfma_f32_16x16x32_bf16 v[62:65], v[58:61], v[82:85], v[62:65]
	v_mfma_f32_16x16x32_bf16 v[146:149], v[74:77], v[82:85], v[146:149]
	v_mfma_f32_16x16x32_bf16 v[66:69], v[58:61], v[194:197], v[66:69]
	v_mfma_f32_16x16x32_bf16 v[154:157], v[74:77], v[194:197], v[154:157]
	v_mfma_f32_16x16x32_bf16 v[138:141], v[58:61], v[202:205], v[138:141]
	v_mfma_f32_16x16x32_bf16 v[134:137], v[74:77], v[202:205], v[134:137]
	v_mfma_f32_16x16x32_bf16 v[122:125], v[58:61], v[210:213], v[122:125]
	v_mfma_f32_16x16x32_bf16 v[118:121], v[74:77], v[210:213], v[118:121]
	v_mfma_f32_16x16x32_bf16 v[150:153], v[174:177], v[78:81], v[150:153]
	v_mfma_f32_16x16x32_bf16 v[78:81], v[182:185], v[78:81], v[142:145]
	v_mfma_f32_16x16x32_bf16 v[142:145], v[186:189], v[82:85], v[78:81]
	v_mfma_f32_16x16x32_bf16 v[78:81], v[174:177], v[190:193], v[130:133]
	v_mfma_f32_16x16x32_bf16 v[130:133], v[178:181], v[194:197], v[78:81]
	v_mfma_f32_16x16x32_bf16 v[78:81], v[182:185], v[190:193], v[126:129]
	v_mfma_f32_16x16x32_bf16 v[126:129], v[186:189], v[194:197], v[78:81]
	v_mfma_f32_16x16x32_bf16 v[78:81], v[174:177], v[198:201], v[114:117]
	v_mfma_f32_16x16x32_bf16 v[114:117], v[178:181], v[202:205], v[78:81]
	v_mfma_f32_16x16x32_bf16 v[78:81], v[182:185], v[198:201], v[110:113]
	v_mfma_f32_16x16x32_bf16 v[110:113], v[186:189], v[202:205], v[78:81]
	v_mfma_f32_16x16x32_bf16 v[78:81], v[174:177], v[206:209], v[106:109]
	v_mfma_f32_16x16x32_bf16 v[106:109], v[178:181], v[210:213], v[78:81]
	v_mfma_f32_16x16x32_bf16 v[78:81], v[182:185], v[206:209], v[102:105]
	v_mfma_f32_16x16x32_bf16 v[150:153], v[178:181], v[82:85], v[150:153]
	v_mfma_f32_16x16x32_bf16 v[102:105], v[186:189], v[210:213], v[78:81]
	s_barrier
; #define PG8_STAGE(bufoff, gbase, voff) do { _Pragma("unroll") for (int _i = 0; _i < 2; ++_i) \
;         __builtin_amdgcn_global_load_lds((const unsigned*)((const char*)(gbase) + (voff)[_i]), (PG8_LAS unsigned*)(lds + (bufoff) + ldsw + _i * 8192), 16, 0, 0); } while (0)
; #define PG8_LDA(dst, b, h) do { _Pragma("unroll") for (int m = 0; m < 4; ++m) _Pragma("unroll") for (int k = 0; k < 2; ++k) dst[m][k] = *(const PG8_LAS bf16x8*)(lds + PG8_SA(b, h) + aoff + m * 2048 + k * 1024); } while (0)
; #define PG8_MMA(ai, bj, At, Bt) do { __builtin_amdgcn_s_setprio(1); _Pragma("unroll") for (int m = 0; m < 4; ++m) _Pragma("unroll") for (int n = 0; n < 2; ++n) _Pragma("unroll") for (int k = 0; k < 2; ++k) \
;         acc[ai][bj][m][n] = __builtin_amdgcn_mfma_f32_16x16x32_bf16(Bt[n][k], At[m][k], acc[ai][bj][m][n], 0, 0, 0); __builtin_amdgcn_s_setprio(0); } while (0)
; #define PG8_WAIT_V(n) asm volatile("s_waitcnt vmcnt(" #n ")" ::: "memory")
; #define PG8_WAIT_L(n) asm volatile("s_waitcnt lgkmcnt(" #n ")" ::: "memory")
; #define PG8_BAR __builtin_amdgcn_s_barrier()
; #define PG8_SCHED __builtin_amdgcn_sched_barrier(0)
; template <class Epi, class Sched, bool ALIGN_EPI = false, bool SP2 = false>
; __device__ __forceinline__ void gemm_phase(PG8_LAS unsigned char* lds, const Gemm g, const Sched& S, const Epi& E, const int tid) {
;     ...
;             PG8_LDA(At, 1, 1); PG8_STAGE(PG8_SB(1, 0), b3, voffB); PG8_STAGE(PG8_SB(1, 1), b3 + hstep, voffB); PG8_STAGE(PG8_SA(1, 0), a3, voffA);
;             PG8_WAIT_V(8); PG8_WAIT_L(0); PG8_BAR; PG8_MMA(1, 0, At, B0); PG8_MMA(1, 1, At, B1); PG8_BAR; PG8_SCHED;
;     ...
;         if constexpr (ALIGN_EPI) { if (wr == 0) PG8_BAR; }
	s_add_i32 s26, s26, s67
	v_lshl_add_u64 v[82:83], v[160:161], 0, s[16:17]
	s_mov_b32 m0, s26
	s_nop 0
	ds_read_b128 v[78:81], v243 offset:49152
	ds_read_b128 v[190:193], v243 offset:50176
	ds_read_b128 v[194:197], v243 offset:51200
	ds_read_b128 v[198:201], v243 offset:52224
	ds_read_b128 v[202:205], v243 offset:53248
	ds_read_b128 v[206:209], v243 offset:54272
	ds_read_b128 v[210:213], v243 offset:55296
	ds_read_b128 v[244:247], v243 offset:56320
	global_load_lds_dwordx4 v[82:83], off
	s_add_i32 m0, s26, 0x2000
	s_add_u32 s60, s60, 0x40080
	v_lshl_add_u64 v[82:83], v[214:215], 0, s[16:17]
	s_addc_u32 s61, s61, 0
	s_add_i32 s26, s27, s67
	global_load_lds_dwordx4 v[82:83], off
	v_lshl_add_u64 v[82:83], s[60:61], 0, v[164:165]
	s_mov_b32 m0, s26
	s_nop 0
	global_load_lds_dwordx4 v[82:83], off
	v_lshl_add_u64 v[82:83], s[60:61], 0, v[168:169]
	s_add_i32 m0, s26, 0x2000
	s_nop 0
	global_load_lds_dwordx4 v[82:83], off
	v_lshl_add_u64 v[82:83], v[248:249], 0, s[16:17]
	s_mov_b32 m0, s72
	s_nop 0
	global_load_lds_dwordx4 v[82:83], off
	v_lshl_add_u64 v[82:83], v[250:251], 0, s[16:17]
	s_mov_b32 m0, s73
	s_nop 0
	global_load_lds_dwordx4 v[82:83], off
	s_waitcnt vmcnt(8)
	s_waitcnt lgkmcnt(0)
	s_barrier
	s_waitcnt lgkmcnt(0)
	v_mfma_f32_16x16x32_bf16 v[82:85], v[54:57], v[78:81], v[90:93]
	v_mfma_f32_16x16x32_bf16 v[90:93], v[58:61], v[190:193], v[82:85]
	v_mfma_f32_16x16x32_bf16 v[82:85], v[70:73], v[78:81], v[86:89]
	v_mfma_f32_16x16x32_bf16 v[86:89], v[74:77], v[190:193], v[82:85]
	v_mfma_f32_16x16x32_bf16 v[82:85], v[54:57], v[194:197], v[98:101]
	v_mfma_f32_16x16x32_bf16 v[98:101], v[58:61], v[198:201], v[82:85]
	v_mfma_f32_16x16x32_bf16 v[82:85], v[70:73], v[194:197], v[94:97]
	v_mfma_f32_16x16x32_bf16 v[42:45], v[54:57], v[202:205], v[42:45]
	v_mfma_f32_16x16x32_bf16 v[38:41], v[70:73], v[202:205], v[38:41]
	v_mfma_f32_16x16x32_bf16 v[26:29], v[54:57], v[210:213], v[26:29]
	v_mfma_f32_16x16x32_bf16 v[22:25], v[70:73], v[210:213], v[22:25]
	v_mfma_f32_16x16x32_bf16 v[94:97], v[74:77], v[198:201], v[82:85]
	v_mfma_f32_16x16x32_bf16 v[42:45], v[58:61], v[206:209], v[42:45]
	v_mfma_f32_16x16x32_bf16 v[38:41], v[74:77], v[206:209], v[38:41]
	v_mfma_f32_16x16x32_bf16 v[26:29], v[58:61], v[244:247], v[26:29]
	v_mfma_f32_16x16x32_bf16 v[22:25], v[74:77], v[244:247], v[22:25]
	v_mfma_f32_16x16x32_bf16 v[46:49], v[174:177], v[78:81], v[46:49]
	v_mfma_f32_16x16x32_bf16 v[82:85], v[178:181], v[190:193], v[46:49]
	v_mfma_f32_16x16x32_bf16 v[46:49], v[182:185], v[78:81], v[50:53]
	v_mfma_f32_16x16x32_bf16 v[34:37], v[174:177], v[194:197], v[34:37]
	v_mfma_f32_16x16x32_bf16 v[30:33], v[182:185], v[194:197], v[30:33]
	v_mfma_f32_16x16x32_bf16 v[18:21], v[174:177], v[202:205], v[18:21]
	v_mfma_f32_16x16x32_bf16 v[14:17], v[182:185], v[202:205], v[14:17]
	v_mfma_f32_16x16x32_bf16 v[10:13], v[174:177], v[210:213], v[10:13]
	v_mfma_f32_16x16x32_bf16 v[6:9], v[182:185], v[210:213], v[6:9]
	v_mfma_f32_16x16x32_bf16 v[78:81], v[186:189], v[190:193], v[46:49]
	v_mfma_f32_16x16x32_bf16 v[34:37], v[178:181], v[198:201], v[34:37]
	v_mfma_f32_16x16x32_bf16 v[30:33], v[186:189], v[198:201], v[30:33]
	v_mfma_f32_16x16x32_bf16 v[18:21], v[178:181], v[206:209], v[18:21]
	v_mfma_f32_16x16x32_bf16 v[14:17], v[186:189], v[206:209], v[14:17]
	v_mfma_f32_16x16x32_bf16 v[10:13], v[178:181], v[244:247], v[10:13]
	v_mfma_f32_16x16x32_bf16 v[6:9], v[186:189], v[244:247], v[6:9]
	s_add_i32 s34, s34, 2
	s_add_u32 s44, s44, 0x100
	s_addc_u32 s45, s45, 0
	s_add_u32 s19, s19, 0x100
	s_addc_u32 s33, s33, 0
	s_cmp_gt_u32 s34, 13
	s_barrier
	s_cbranch_scc0 .LBB0_641
	s_and_b64 vcc, exec, s[50:51]
	s_cbranch_vccz .LBB0_644
	s_barrier

; #define PG8_STAGE(bufoff, gbase, voff) do { _Pragma("unroll") for (int _i = 0; _i < 2; ++_i) \
;         __builtin_amdgcn_global_load_lds((const unsigned*)((const char*)(gbase) + (voff)[_i]), (PG8_LAS unsigned*)(lds + (bufoff) + ldsw + _i * 8192), 16, 0, 0); } while (0)
; #define PG8_LDA(dst, b, h) do { _Pragma("unroll") for (int m = 0; m < 4; ++m) _Pragma("unroll") for (int k = 0; k < 2; ++k) dst[m][k] = *(const PG8_LAS bf16x8*)(lds + PG8_SA(b, h) + aoff + m * 2048 + k * 1024); } while (0)
; #define PG8_LDB(dst, b, h) do { _Pragma("unroll") for (int n = 0; n < 2; ++n) _Pragma("unroll") for (int k = 0; k < 2; ++k) dst[n][k] = *(const PG8_LAS bf16x8*)(lds + PG8_SB(b, h) + boff + n * 2048 + k * 1024); } while (0)
; #define PG8_MMA(ai, bj, At, Bt) do { __builtin_amdgcn_s_setprio(1); _Pragma("unroll") for (int m = 0; m < 4; ++m) _Pragma("unroll") for (int n = 0; n < 2; ++n) _Pragma("unroll") for (int k = 0; k < 2; ++k) \
;         acc[ai][bj][m][n] = __builtin_amdgcn_mfma_f32_16x16x32_bf16(Bt[n][k], At[m][k], acc[ai][bj][m][n], 0, 0, 0); __builtin_amdgcn_s_setprio(0); } while (0)
; #define PG8_WAIT_V(n) asm volatile("s_waitcnt vmcnt(" #n ")" ::: "memory")
; #define PG8_WAIT_L(n) asm volatile("s_waitcnt lgkmcnt(" #n ")" ::: "memory")
; #define PG8_BAR __builtin_amdgcn_s_barrier()
; #define PG8_SCHED __builtin_amdgcn_sched_barrier(0)
; template <class Epi, class Sched, bool ALIGN_EPI = false, bool SP2 = false>
; __device__ __forceinline__ void gemm_phase(PG8_LAS unsigned char* lds, const Gemm g, const Sched& S, const Epi& E, const int tid) {
;     ...
;             const bool last = (t == nt - 2);
;             const char* a1 = cA + (size_t)(t + 1) * kstep;
;             const char* a2 = last ? nA : cA + (size_t)(t + 2) * kstep; const char* b2 = last ? nB : cB + (size_t)(t + 2) * kstep;
;             const char* a3 = a2 + kstep; const char* b3 = b2 + kstep;
;             if (last && has_next) S.a_ready(nxt);
;             if constexpr (SP2) {
;             PG8_LDB(B0, 0, 0); PG8_LDB(B1, 0, 1); PG8_SCHED; PG8_LDA(At, 0, 0); PG8_STAGE(PG8_SA(1, 1), a1 + hstep, voffA);
;             PG8_WAIT_V(8); PG8_WAIT_L(0); PG8_BAR; PG8_MMA(0, 0, At, B0); PG8_MMA(0, 1, At, B1); PG8_BAR; PG8_SCHED;
;             PG8_LDA(At, 0, 1); PG8_STAGE(PG8_SB(0, 0), b2, voffB); PG8_STAGE(PG8_SB(0, 1), b2 + hstep, voffB); PG8_STAGE(PG8_SA(0, 0), a2, voffA);
.LBB0_760:
	s_add_u32 s14, s12, 0x100
	s_addc_u32 s15, s13, 0
	s_add_i32 s26, 0, 0x10000
	s_cmp_eq_u32 s33, 40
	s_cselect_b32 s39, s5, s15
	s_cselect_b32 s38, s4, s14
	v_add_u32_e32 v148, s26, v5
	s_cselect_b32 s37, s11, s19
	s_cselect_b32 s36, s10, s18
	s_add_i32 s27, 0, 0x14000
	ds_read_b128 v[144:147], v148
	ds_read_b128 v[152:155], v148 offset:1024
	ds_read_b128 v[164:167], v148 offset:2048
	ds_read_b128 v[168:171], v148 offset:3072
	v_add_u32_e32 v148, s27, v5
	ds_read_b128 v[172:175], v148
	ds_read_b128 v[176:179], v148 offset:1024
	ds_read_b128 v[180:183], v148 offset:2048
	ds_read_b128 v[184:187], v148 offset:3072
	v_lshl_add_u64 v[148:149], s[12:13], 0, v[140:141]
	s_add_i32 m0, s41, 0xc000
	ds_read_b128 v[188:191], v151
	ds_read_b128 v[192:195], v151 offset:1024
	ds_read_b128 v[196:199], v151 offset:2048
	ds_read_b128 v[200:203], v151 offset:3072
	ds_read_b128 v[204:207], v151 offset:4096
	ds_read_b128 v[208:211], v151 offset:5120
	ds_read_b128 v[218:221], v151 offset:6144
	ds_read_b128 v[222:225], v151 offset:7168
	global_load_lds_dwordx4 v[148:149], off
	v_lshl_add_u64 v[148:149], s[12:13], 0, v[142:143]
	s_add_i32 m0, s41, 0xe000
	s_nop 0
	global_load_lds_dwordx4 v[148:149], off
	s_waitcnt vmcnt(8)
	s_waitcnt lgkmcnt(0)
	s_barrier
	s_waitcnt lgkmcnt(0)
	v_mfma_f32_16x16x32_bf16 v[130:133], v[144:147], v[188:191], v[130:133]
	v_mfma_f32_16x16x32_bf16 v[126:129], v[164:167], v[188:191], v[126:129]
	v_mfma_f32_16x16x32_bf16 v[114:117], v[144:147], v[196:199], v[114:117]
	v_mfma_f32_16x16x32_bf16 v[110:113], v[164:167], v[196:199], v[110:113]
	v_mfma_f32_16x16x32_bf16 v[98:101], v[144:147], v[204:207], v[98:101]
	v_mfma_f32_16x16x32_bf16 v[94:97], v[164:167], v[204:207], v[94:97]
	v_mfma_f32_16x16x32_bf16 v[82:85], v[144:147], v[218:221], v[82:85]
	v_mfma_f32_16x16x32_bf16 v[78:81], v[164:167], v[218:221], v[78:81]
	v_mfma_f32_16x16x32_bf16 v[130:133], v[152:155], v[192:195], v[130:133]
	v_mfma_f32_16x16x32_bf16 v[126:129], v[168:171], v[192:195], v[126:129]
	v_mfma_f32_16x16x32_bf16 v[114:117], v[152:155], v[200:203], v[114:117]
	v_mfma_f32_16x16x32_bf16 v[110:113], v[168:171], v[200:203], v[110:113]
	v_mfma_f32_16x16x32_bf16 v[98:101], v[152:155], v[208:211], v[98:101]
	v_mfma_f32_16x16x32_bf16 v[94:97], v[168:171], v[208:211], v[94:97]
	v_mfma_f32_16x16x32_bf16 v[82:85], v[152:155], v[222:225], v[82:85]
	v_mfma_f32_16x16x32_bf16 v[78:81], v[168:171], v[222:225], v[78:81]
	v_mfma_f32_16x16x32_bf16 v[122:125], v[172:175], v[188:191], v[122:125]
	v_mfma_f32_16x16x32_bf16 v[118:121], v[180:183], v[188:191], v[118:121]
	v_mfma_f32_16x16x32_bf16 v[106:109], v[172:175], v[196:199], v[106:109]
	v_mfma_f32_16x16x32_bf16 v[102:105], v[180:183], v[196:199], v[102:105]
	v_mfma_f32_16x16x32_bf16 v[90:93], v[172:175], v[204:207], v[90:93]
	v_mfma_f32_16x16x32_bf16 v[86:89], v[180:183], v[204:207], v[86:89]
	v_mfma_f32_16x16x32_bf16 v[74:77], v[172:175], v[218:221], v[74:77]
	v_mfma_f32_16x16x32_bf16 v[70:73], v[180:183], v[218:221], v[70:73]
	v_mfma_f32_16x16x32_bf16 v[122:125], v[176:179], v[192:195], v[122:125]
	v_mfma_f32_16x16x32_bf16 v[118:121], v[184:187], v[192:195], v[118:121]
	v_mfma_f32_16x16x32_bf16 v[106:109], v[176:179], v[200:203], v[106:109]
	v_mfma_f32_16x16x32_bf16 v[102:105], v[184:187], v[200:203], v[102:105]
	v_mfma_f32_16x16x32_bf16 v[90:93], v[176:179], v[208:211], v[90:93]
	v_mfma_f32_16x16x32_bf16 v[86:89], v[184:187], v[208:211], v[86:89]
	v_mfma_f32_16x16x32_bf16 v[74:77], v[176:179], v[222:225], v[74:77]
	v_mfma_f32_16x16x32_bf16 v[70:73], v[184:187], v[222:225], v[70:73]
	s_barrier
	s_add_i32 s12, s26, s40
	v_lshl_add_u64 v[148:149], s[36:37], 0, v[134:135]
	s_mov_b32 m0, s12
	ds_read_b128 v[188:191], v151 offset:16384
	ds_read_b128 v[192:195], v151 offset:17408
	ds_read_b128 v[196:199], v151 offset:18432
	ds_read_b128 v[200:203], v151 offset:19456
	ds_read_b128 v[204:207], v151 offset:20480
	ds_read_b128 v[208:211], v151 offset:21504
	ds_read_b128 v[218:221], v151 offset:22528
	ds_read_b128 v[222:225], v151 offset:23552
	global_load_lds_dwordx4 v[148:149], off
	s_add_i32 m0, s12, 0x2000
	s_add_u32 s12, s36, 0xb0000
	v_lshl_add_u64 v[156:157], s[36:37], 0, v[138:139]
	s_addc_u32 s13, s37, 0
	s_add_i32 s26, s27, s40
	global_load_lds_dwordx4 v[156:157], off
	v_lshl_add_u64 v[160:161], s[12:13], 0, v[134:135]
	s_mov_b32 m0, s26
	v_lshl_add_u64 v[212:213], s[38:39], 0, v[136:137]
	global_load_lds_dwordx4 v[160:161], off
	v_lshl_add_u64 v[160:161], s[12:13], 0, v[138:139]
	s_add_i32 m0, s26, 0x2000
	s_nop 0
	global_load_lds_dwordx4 v[160:161], off
	v_lshl_add_u64 v[160:161], s[38:39], 0, v[2:3]
	s_mov_b32 m0, s41
	s_nop 0
	global_load_lds_dwordx4 v[160:161], off
	s_mov_b32 m0, s42
	s_nop 0
	global_load_lds_dwordx4 v[212:213], off
	s_waitcnt vmcnt(8)
	s_waitcnt lgkmcnt(0)
	s_barrier
; #define PG8_STAGE(bufoff, gbase, voff) do { _Pragma("unroll") for (int _i = 0; _i < 2; ++_i) \
;         __builtin_amdgcn_global_load_lds((const unsigned*)((const char*)(gbase) + (voff)[_i]), (PG8_LAS unsigned*)(lds + (bufoff) + ldsw + _i * 8192), 16, 0, 0); } while (0)
; #define PG8_LDA(dst, b, h) do { _Pragma("unroll") for (int m = 0; m < 4; ++m) _Pragma("unroll") for (int k = 0; k < 2; ++k) dst[m][k] = *(const PG8_LAS bf16x8*)(lds + PG8_SA(b, h) + aoff + m * 2048 + k * 1024); } while (0)
; #define PG8_LDB(dst, b, h) do { _Pragma("unroll") for (int n = 0; n < 2; ++n) _Pragma("unroll") for (int k = 0; k < 2; ++k) dst[n][k] = *(const PG8_LAS bf16x8*)(lds + PG8_SB(b, h) + boff + n * 2048 + k * 1024); } while (0)
; #define PG8_MMA(ai, bj, At, Bt) do { __builtin_amdgcn_s_setprio(1); _Pragma("unroll") for (int m = 0; m < 4; ++m) _Pragma("unroll") for (int n = 0; n < 2; ++n) _Pragma("unroll") for (int k = 0; k < 2; ++k) \
;         acc[ai][bj][m][n] = __builtin_amdgcn_mfma_f32_16x16x32_bf16(Bt[n][k], At[m][k], acc[ai][bj][m][n], 0, 0, 0); __builtin_amdgcn_s_setprio(0); } while (0)
; #define PG8_WAIT_V(n) asm volatile("s_waitcnt vmcnt(" #n ")" ::: "memory")
; #define PG8_WAIT_L(n) asm volatile("s_waitcnt lgkmcnt(" #n ")" ::: "memory")
; #define PG8_BAR __builtin_amdgcn_s_barrier()
; #define PG8_SCHED __builtin_amdgcn_sched_barrier(0)
; template <class Epi, class Sched, bool ALIGN_EPI = false, bool SP2 = false>
; __device__ __forceinline__ void gemm_phase(PG8_LAS unsigned char* lds, const Gemm g, const Sched& S, const Epi& E, const int tid) {
;     ...
;             PG8_WAIT_V(8); PG8_WAIT_L(0); PG8_BAR; PG8_MMA(1, 0, At, B0); PG8_MMA(1, 1, At, B1); PG8_BAR; PG8_SCHED;
;             PG8_LDB(B0, 1, 0); PG8_LDB(B1, 1, 1); PG8_SCHED; PG8_LDA(At, 1, 0); PG8_STAGE(PG8_SA(0, 1), a2 + hstep, voffA);
;             PG8_WAIT_V(8); PG8_WAIT_L(0); PG8_BAR; PG8_MMA(0, 0, At, B0); PG8_MMA(0, 1, At, B1); PG8_BAR; PG8_SCHED;
	s_waitcnt lgkmcnt(0)
	v_mfma_f32_16x16x32_bf16 v[66:69], v[144:147], v[188:191], v[66:69]
	v_mfma_f32_16x16x32_bf16 v[62:65], v[164:167], v[188:191], v[62:65]
	v_mfma_f32_16x16x32_bf16 v[50:53], v[144:147], v[196:199], v[50:53]
	v_mfma_f32_16x16x32_bf16 v[46:49], v[164:167], v[196:199], v[46:49]
	v_mfma_f32_16x16x32_bf16 v[34:37], v[144:147], v[204:207], v[34:37]
	v_mfma_f32_16x16x32_bf16 v[30:33], v[164:167], v[204:207], v[30:33]
	v_mfma_f32_16x16x32_bf16 v[18:21], v[144:147], v[218:221], v[18:21]
	v_mfma_f32_16x16x32_bf16 v[14:17], v[164:167], v[218:221], v[14:17]
	v_mfma_f32_16x16x32_bf16 v[66:69], v[152:155], v[192:195], v[66:69]
	v_mfma_f32_16x16x32_bf16 v[62:65], v[168:171], v[192:195], v[62:65]
	v_mfma_f32_16x16x32_bf16 v[50:53], v[152:155], v[200:203], v[50:53]
	v_mfma_f32_16x16x32_bf16 v[46:49], v[168:171], v[200:203], v[46:49]
	v_mfma_f32_16x16x32_bf16 v[34:37], v[152:155], v[208:211], v[34:37]
	v_mfma_f32_16x16x32_bf16 v[30:33], v[168:171], v[208:211], v[30:33]
	v_mfma_f32_16x16x32_bf16 v[18:21], v[152:155], v[222:225], v[18:21]
	v_mfma_f32_16x16x32_bf16 v[14:17], v[168:171], v[222:225], v[14:17]
	v_mfma_f32_16x16x32_bf16 v[58:61], v[172:175], v[188:191], v[58:61]
	v_mfma_f32_16x16x32_bf16 v[54:57], v[180:183], v[188:191], v[54:57]
	v_mfma_f32_16x16x32_bf16 v[42:45], v[172:175], v[196:199], v[42:45]
	v_mfma_f32_16x16x32_bf16 v[38:41], v[180:183], v[196:199], v[38:41]
	v_mfma_f32_16x16x32_bf16 v[26:29], v[172:175], v[204:207], v[26:29]
	v_mfma_f32_16x16x32_bf16 v[22:25], v[180:183], v[204:207], v[22:25]
	v_mfma_f32_16x16x32_bf16 v[10:13], v[172:175], v[218:221], v[10:13]
	v_mfma_f32_16x16x32_bf16 v[6:9], v[180:183], v[218:221], v[6:9]
	v_mfma_f32_16x16x32_bf16 v[58:61], v[176:179], v[192:195], v[58:61]
	v_mfma_f32_16x16x32_bf16 v[54:57], v[184:187], v[192:195], v[54:57]
	v_mfma_f32_16x16x32_bf16 v[42:45], v[176:179], v[200:203], v[42:45]
	v_mfma_f32_16x16x32_bf16 v[38:41], v[184:187], v[200:203], v[38:41]
	v_mfma_f32_16x16x32_bf16 v[26:29], v[176:179], v[208:211], v[26:29]
	v_mfma_f32_16x16x32_bf16 v[22:25], v[184:187], v[208:211], v[22:25]
	v_mfma_f32_16x16x32_bf16 v[10:13], v[176:179], v[222:225], v[10:13]
	v_mfma_f32_16x16x32_bf16 v[6:9], v[184:187], v[222:225], v[6:9]
	s_barrier
	s_add_i32 s26, 0, 0x18000
	v_add_u32_e32 v159, s26, v5
	s_add_i32 s27, 0, 0x1c000
	ds_read_b128 v[144:147], v159
	ds_read_b128 v[152:155], v159 offset:1024
	ds_read_b128 v[164:167], v159 offset:2048
	ds_read_b128 v[168:171], v159 offset:3072
	v_add_u32_e32 v159, s27, v5
	ds_read_b128 v[172:175], v159
	ds_read_b128 v[176:179], v159 offset:1024
	ds_read_b128 v[180:183], v159 offset:2048
	ds_read_b128 v[184:187], v159 offset:3072
	s_add_u32 s12, s38, 0xb0000
	s_addc_u32 s13, s39, 0
	s_mov_b32 m0, s43
	v_lshl_add_u64 v[214:215], s[12:13], 0, v[2:3]
	ds_read_b128 v[188:191], v151 offset:32768
	ds_read_b128 v[192:195], v151 offset:33792
	ds_read_b128 v[196:199], v151 offset:34816
	ds_read_b128 v[200:203], v151 offset:35840
	ds_read_b128 v[204:207], v151 offset:36864
	ds_read_b128 v[208:211], v151 offset:37888
	ds_read_b128 v[218:221], v151 offset:38912
	ds_read_b128 v[222:225], v151 offset:39936
	global_load_lds_dwordx4 v[214:215], off
	v_lshl_add_u64 v[214:215], s[12:13], 0, v[136:137]
	s_mov_b32 m0, s44
	s_nop 0
	global_load_lds_dwordx4 v[214:215], off
	s_waitcnt vmcnt(8)
	s_waitcnt lgkmcnt(0)
	s_barrier
	s_waitcnt lgkmcnt(0)
	v_mfma_f32_16x16x32_bf16 v[130:133], v[144:147], v[188:191], v[130:133]
	v_mfma_f32_16x16x32_bf16 v[126:129], v[164:167], v[188:191], v[126:129]
	v_mfma_f32_16x16x32_bf16 v[114:117], v[144:147], v[196:199], v[114:117]
	v_mfma_f32_16x16x32_bf16 v[110:113], v[164:167], v[196:199], v[110:113]
	v_mfma_f32_16x16x32_bf16 v[98:101], v[144:147], v[204:207], v[98:101]
	v_mfma_f32_16x16x32_bf16 v[94:97], v[164:167], v[204:207], v[94:97]
	v_mfma_f32_16x16x32_bf16 v[82:85], v[144:147], v[218:221], v[82:85]
	v_mfma_f32_16x16x32_bf16 v[78:81], v[164:167], v[218:221], v[78:81]
	v_mfma_f32_16x16x32_bf16 v[130:133], v[152:155], v[192:195], v[130:133]
	v_mfma_f32_16x16x32_bf16 v[126:129], v[168:171], v[192:195], v[126:129]
	v_mfma_f32_16x16x32_bf16 v[114:117], v[152:155], v[200:203], v[114:117]
	v_mfma_f32_16x16x32_bf16 v[110:113], v[168:171], v[200:203], v[110:113]
	v_mfma_f32_16x16x32_bf16 v[98:101], v[152:155], v[208:211], v[98:101]
	v_mfma_f32_16x16x32_bf16 v[94:97], v[168:171], v[208:211], v[94:97]
	v_mfma_f32_16x16x32_bf16 v[82:85], v[152:155], v[222:225], v[82:85]
	v_mfma_f32_16x16x32_bf16 v[78:81], v[168:171], v[222:225], v[78:81]
	v_mfma_f32_16x16x32_bf16 v[122:125], v[172:175], v[188:191], v[122:125]
	v_mfma_f32_16x16x32_bf16 v[118:121], v[180:183], v[188:191], v[118:121]
	v_mfma_f32_16x16x32_bf16 v[106:109], v[172:175], v[196:199], v[106:109]
	v_mfma_f32_16x16x32_bf16 v[102:105], v[180:183], v[196:199], v[102:105]
	v_mfma_f32_16x16x32_bf16 v[90:93], v[172:175], v[204:207], v[90:93]
	v_mfma_f32_16x16x32_bf16 v[86:89], v[180:183], v[204:207], v[86:89]
	v_mfma_f32_16x16x32_bf16 v[74:77], v[172:175], v[218:221], v[74:77]
	v_mfma_f32_16x16x32_bf16 v[70:73], v[180:183], v[218:221], v[70:73]
	v_mfma_f32_16x16x32_bf16 v[122:125], v[176:179], v[192:195], v[122:125]
	v_mfma_f32_16x16x32_bf16 v[118:121], v[184:187], v[192:195], v[118:121]
	v_mfma_f32_16x16x32_bf16 v[106:109], v[176:179], v[200:203], v[106:109]
	v_mfma_f32_16x16x32_bf16 v[102:105], v[184:187], v[200:203], v[102:105]
	v_mfma_f32_16x16x32_bf16 v[90:93], v[176:179], v[208:211], v[90:93]
	v_mfma_f32_16x16x32_bf16 v[86:89], v[184:187], v[208:211], v[86:89]
	v_mfma_f32_16x16x32_bf16 v[74:77], v[176:179], v[222:225], v[74:77]
	v_mfma_f32_16x16x32_bf16 v[70:73], v[184:187], v[222:225], v[70:73]
	s_barrier
; #define PG8_STAGE(bufoff, gbase, voff) do { _Pragma("unroll") for (int _i = 0; _i < 2; ++_i) \
;         __builtin_amdgcn_global_load_lds((const unsigned*)((const char*)(gbase) + (voff)[_i]), (PG8_LAS unsigned*)(lds + (bufoff) + ldsw + _i * 8192), 16, 0, 0); } while (0)
; #define PG8_LDA(dst, b, h) do { _Pragma("unroll") for (int m = 0; m < 4; ++m) _Pragma("unroll") for (int k = 0; k < 2; ++k) dst[m][k] = *(const PG8_LAS bf16x8*)(lds + PG8_SA(b, h) + aoff + m * 2048 + k * 1024); } while (0)
; #define PG8_MMA(ai, bj, At, Bt) do { __builtin_amdgcn_s_setprio(1); _Pragma("unroll") for (int m = 0; m < 4; ++m) _Pragma("unroll") for (int n = 0; n < 2; ++n) _Pragma("unroll") for (int k = 0; k < 2; ++k) \
;         acc[ai][bj][m][n] = __builtin_amdgcn_mfma_f32_16x16x32_bf16(Bt[n][k], At[m][k], acc[ai][bj][m][n], 0, 0, 0); __builtin_amdgcn_s_setprio(0); } while (0)
; #define PG8_WAIT_V(n) asm volatile("s_waitcnt vmcnt(" #n ")" ::: "memory")
; #define PG8_WAIT_L(n) asm volatile("s_waitcnt lgkmcnt(" #n ")" ::: "memory")
; #define PG8_BAR __builtin_amdgcn_s_barrier()
; #define PG8_SCHED __builtin_amdgcn_sched_barrier(0)
; template <class Epi, class Sched, bool ALIGN_EPI = false, bool SP2 = false>
; __device__ __forceinline__ void gemm_phase(PG8_LAS unsigned char* lds, const Gemm g, const Sched& S, const Epi& E, const int tid) {
;     ...
;             PG8_LDA(At, 1, 1); PG8_STAGE(PG8_SB(1, 0), b3, voffB); PG8_STAGE(PG8_SB(1, 1), b3 + hstep, voffB); PG8_STAGE(PG8_SA(1, 0), a3, voffA);
;             PG8_WAIT_V(8); PG8_WAIT_L(0); PG8_BAR; PG8_MMA(1, 0, At, B0); PG8_MMA(1, 1, At, B1); PG8_BAR; PG8_SCHED;
;     ...
;         if constexpr (ALIGN_EPI) { if (wr == 0) PG8_BAR; }
	s_add_i32 s12, s26, s40
	v_lshl_add_u64 v[148:149], v[148:149], 0, s[16:17]
	s_mov_b32 m0, s12
	ds_read_b128 v[188:191], v151 offset:49152
	ds_read_b128 v[192:195], v151 offset:50176
	ds_read_b128 v[196:199], v151 offset:51200
	ds_read_b128 v[200:203], v151 offset:52224
	ds_read_b128 v[204:207], v151 offset:53248
	ds_read_b128 v[208:211], v151 offset:54272
	ds_read_b128 v[218:221], v151 offset:55296
	ds_read_b128 v[222:225], v151 offset:56320
	global_load_lds_dwordx4 v[148:149], off
	s_add_i32 m0, s12, 0x2000
	s_add_u32 s12, s36, 0xb0080
	v_lshl_add_u64 v[148:149], v[156:157], 0, s[16:17]
	s_addc_u32 s13, s37, 0
	s_add_i32 s26, s27, s40
	global_load_lds_dwordx4 v[148:149], off
	v_lshl_add_u64 v[148:149], s[12:13], 0, v[134:135]
	s_mov_b32 m0, s26
	s_nop 0
	global_load_lds_dwordx4 v[148:149], off
	v_lshl_add_u64 v[148:149], s[12:13], 0, v[138:139]
	s_add_i32 m0, s26, 0x2000
	s_nop 0
	global_load_lds_dwordx4 v[148:149], off
	v_lshl_add_u64 v[148:149], v[160:161], 0, s[16:17]
	s_mov_b32 m0, s45
	s_nop 0
	global_load_lds_dwordx4 v[148:149], off
	v_lshl_add_u64 v[148:149], v[212:213], 0, s[16:17]
	s_mov_b32 m0, s46
	s_nop 0
	global_load_lds_dwordx4 v[148:149], off
	s_waitcnt vmcnt(8)
	s_waitcnt lgkmcnt(0)
	s_barrier
	s_waitcnt lgkmcnt(0)
	v_mfma_f32_16x16x32_bf16 v[66:69], v[144:147], v[188:191], v[66:69]
	v_mfma_f32_16x16x32_bf16 v[62:65], v[164:167], v[188:191], v[62:65]
	v_mfma_f32_16x16x32_bf16 v[50:53], v[144:147], v[196:199], v[50:53]
	v_mfma_f32_16x16x32_bf16 v[46:49], v[164:167], v[196:199], v[46:49]
	v_mfma_f32_16x16x32_bf16 v[34:37], v[144:147], v[204:207], v[34:37]
	v_mfma_f32_16x16x32_bf16 v[30:33], v[164:167], v[204:207], v[30:33]
	v_mfma_f32_16x16x32_bf16 v[18:21], v[144:147], v[218:221], v[18:21]
	v_mfma_f32_16x16x32_bf16 v[14:17], v[164:167], v[218:221], v[14:17]
	v_mfma_f32_16x16x32_bf16 v[66:69], v[152:155], v[192:195], v[66:69]
	v_mfma_f32_16x16x32_bf16 v[62:65], v[168:171], v[192:195], v[62:65]
	v_mfma_f32_16x16x32_bf16 v[50:53], v[152:155], v[200:203], v[50:53]
	v_mfma_f32_16x16x32_bf16 v[46:49], v[168:171], v[200:203], v[46:49]
	v_mfma_f32_16x16x32_bf16 v[34:37], v[152:155], v[208:211], v[34:37]
	v_mfma_f32_16x16x32_bf16 v[30:33], v[168:171], v[208:211], v[30:33]
	v_mfma_f32_16x16x32_bf16 v[18:21], v[152:155], v[222:225], v[18:21]
	v_mfma_f32_16x16x32_bf16 v[14:17], v[168:171], v[222:225], v[14:17]
	v_mfma_f32_16x16x32_bf16 v[58:61], v[172:175], v[188:191], v[58:61]
	v_mfma_f32_16x16x32_bf16 v[54:57], v[180:183], v[188:191], v[54:57]
	v_mfma_f32_16x16x32_bf16 v[42:45], v[172:175], v[196:199], v[42:45]
	v_mfma_f32_16x16x32_bf16 v[38:41], v[180:183], v[196:199], v[38:41]
	v_mfma_f32_16x16x32_bf16 v[26:29], v[172:175], v[204:207], v[26:29]
	v_mfma_f32_16x16x32_bf16 v[22:25], v[180:183], v[204:207], v[22:25]
	v_mfma_f32_16x16x32_bf16 v[10:13], v[172:175], v[218:221], v[10:13]
	v_mfma_f32_16x16x32_bf16 v[6:9], v[180:183], v[218:221], v[6:9]
	v_mfma_f32_16x16x32_bf16 v[58:61], v[176:179], v[192:195], v[58:61]
	v_mfma_f32_16x16x32_bf16 v[54:57], v[184:187], v[192:195], v[54:57]
	v_mfma_f32_16x16x32_bf16 v[42:45], v[176:179], v[200:203], v[42:45]
	v_mfma_f32_16x16x32_bf16 v[38:41], v[184:187], v[200:203], v[38:41]
	v_mfma_f32_16x16x32_bf16 v[26:29], v[176:179], v[208:211], v[26:29]
	v_mfma_f32_16x16x32_bf16 v[22:25], v[184:187], v[208:211], v[22:25]
	v_mfma_f32_16x16x32_bf16 v[10:13], v[176:179], v[222:225], v[10:13]
	v_mfma_f32_16x16x32_bf16 v[6:9], v[184:187], v[222:225], v[6:9]
	s_add_i32 s33, s33, 2
	s_add_u32 s18, s18, 0x100
	s_addc_u32 s19, s19, 0
	s_cmp_gt_u32 s33, 41
	s_mov_b64 s[12:13], s[14:15]
	s_barrier
	s_cbranch_scc0 .LBB0_760
	s_and_b64 vcc, exec, s[8:9]
	s_cbranch_vccz .LBB0_763
	s_barrier

; #define PG8_STAGE(bufoff, gbase, voff) do { _Pragma("unroll") for (int _i = 0; _i < 2; ++_i) \
;         __builtin_amdgcn_global_load_lds((const unsigned*)((const char*)(gbase) + (voff)[_i]), (PG8_LAS unsigned*)(lds + (bufoff) + ldsw + _i * 8192), 16, 0, 0); } while (0)
; #define PG8_LDA(dst, b, h) do { _Pragma("unroll") for (int m = 0; m < 4; ++m) _Pragma("unroll") for (int k = 0; k < 2; ++k) dst[m][k] = *(const PG8_LAS bf16x8*)(lds + PG8_SA(b, h) + aoff + m * 2048 + k * 1024); } while (0)
; #define PG8_LDB(dst, b, h) do { _Pragma("unroll") for (int n = 0; n < 2; ++n) _Pragma("unroll") for (int k = 0; k < 2; ++k) dst[n][k] = *(const PG8_LAS bf16x8*)(lds + PG8_SB(b, h) + boff + n * 2048 + k * 1024); } while (0)
; #define PG8_MMA(ai, bj, At, Bt) do { __builtin_amdgcn_s_setprio(1); _Pragma("unroll") for (int m = 0; m < 4; ++m) _Pragma("unroll") for (int n = 0; n < 2; ++n) _Pragma("unroll") for (int k = 0; k < 2; ++k) \
;         acc[ai][bj][m][n] = __builtin_amdgcn_mfma_f32_16x16x32_bf16(Bt[n][k], At[m][k], acc[ai][bj][m][n], 0, 0, 0); __builtin_amdgcn_s_setprio(0); } while (0)
; #define PG8_WAIT_V(n) asm volatile("s_waitcnt vmcnt(" #n ")" ::: "memory")
; #define PG8_WAIT_L(n) asm volatile("s_waitcnt lgkmcnt(" #n ")" ::: "memory")
; #define PG8_BAR __builtin_amdgcn_s_barrier()
; #define PG8_SCHED __builtin_amdgcn_sched_barrier(0)
; template <class Epi, class Sched, bool ALIGN_EPI = false, bool SP2 = false>
; __device__ __forceinline__ void gemm_phase(PG8_LAS unsigned char* lds, const Gemm g, const Sched& S, const Epi& E, const int tid) {
;     ...
;             const bool last = (t == nt - 2);
;             const char* a1 = cA + (size_t)(t + 1) * kstep;
;             const char* a2 = last ? nA : cA + (size_t)(t + 2) * kstep; const char* b2 = last ? nB : cB + (size_t)(t + 2) * kstep;
;             const char* a3 = a2 + kstep; const char* b3 = b2 + kstep;
;             if (last && has_next) S.a_ready(nxt);
;             if constexpr (SP2) {
;             PG8_LDB(B0, 0, 0); PG8_LDB(B1, 0, 1); PG8_SCHED; PG8_LDA(At, 0, 0); PG8_STAGE(PG8_SA(1, 1), a1 + hstep, voffA);
;             PG8_WAIT_V(8); PG8_WAIT_L(0); PG8_BAR; PG8_MMA(0, 0, At, B0); PG8_MMA(0, 1, At, B1); PG8_BAR; PG8_SCHED;
;             PG8_LDA(At, 0, 1); PG8_STAGE(PG8_SB(0, 0), b2, voffB); PG8_STAGE(PG8_SB(0, 1), b2 + hstep, voffB); PG8_STAGE(PG8_SA(0, 0), a2, voffA);
.LBB0_792:
	s_add_u32 s40, s38, 0x100
	s_addc_u32 s41, s39, 0
	s_add_i32 s26, 0, 0x10000
	s_cmp_eq_u32 s19, 40
	s_cselect_b32 s45, s9, s41
	s_cselect_b32 s44, s8, s40
	v_add_u32_e32 v148, s26, v5
	s_cselect_b32 s43, s15, s18
	s_cselect_b32 s42, s14, s1
	s_add_i32 s27, 0, 0x14000
	ds_read_b128 v[144:147], v148
	ds_read_b128 v[174:177], v148 offset:1024
	ds_read_b128 v[178:181], v148 offset:2048
	ds_read_b128 v[182:185], v148 offset:3072
	v_add_u32_e32 v148, s27, v5
	ds_read_b128 v[186:189], v148
	ds_read_b128 v[190:193], v148 offset:1024
	ds_read_b128 v[194:197], v148 offset:2048
	ds_read_b128 v[198:201], v148 offset:3072
	v_lshl_add_u64 v[148:149], s[38:39], 0, v[140:141]
	s_add_i32 m0, s46, 0xc000
	ds_read_b128 v[202:205], v167
	ds_read_b128 v[206:209], v167 offset:1024
	ds_read_b128 v[210:213], v167 offset:2048
	ds_read_b128 v[218:221], v167 offset:3072
	ds_read_b128 v[222:225], v167 offset:4096
	ds_read_b128 v[226:229], v167 offset:5120
	ds_read_b128 v[230:233], v167 offset:6144
	ds_read_b128 v[234:237], v167 offset:7168
	global_load_lds_dwordx4 v[148:149], off
	v_lshl_add_u64 v[148:149], s[38:39], 0, v[142:143]
	s_add_i32 m0, s46, 0xe000
	s_nop 0
	global_load_lds_dwordx4 v[148:149], off
	s_waitcnt vmcnt(8)
	s_waitcnt lgkmcnt(0)
	s_barrier
	s_waitcnt lgkmcnt(0)
	v_mfma_f32_16x16x32_bf16 v[130:133], v[144:147], v[202:205], v[130:133]
	v_mfma_f32_16x16x32_bf16 v[126:129], v[178:181], v[202:205], v[126:129]
	v_mfma_f32_16x16x32_bf16 v[114:117], v[144:147], v[210:213], v[114:117]
	v_mfma_f32_16x16x32_bf16 v[110:113], v[178:181], v[210:213], v[110:113]
	v_mfma_f32_16x16x32_bf16 v[98:101], v[144:147], v[222:225], v[98:101]
	v_mfma_f32_16x16x32_bf16 v[94:97], v[178:181], v[222:225], v[94:97]
	v_mfma_f32_16x16x32_bf16 v[82:85], v[144:147], v[230:233], v[82:85]
	v_mfma_f32_16x16x32_bf16 v[78:81], v[178:181], v[230:233], v[78:81]
	v_mfma_f32_16x16x32_bf16 v[130:133], v[174:177], v[206:209], v[130:133]
	v_mfma_f32_16x16x32_bf16 v[126:129], v[182:185], v[206:209], v[126:129]
	v_mfma_f32_16x16x32_bf16 v[114:117], v[174:177], v[218:221], v[114:117]
	v_mfma_f32_16x16x32_bf16 v[110:113], v[182:185], v[218:221], v[110:113]
	v_mfma_f32_16x16x32_bf16 v[98:101], v[174:177], v[226:229], v[98:101]
	v_mfma_f32_16x16x32_bf16 v[94:97], v[182:185], v[226:229], v[94:97]
	v_mfma_f32_16x16x32_bf16 v[82:85], v[174:177], v[234:237], v[82:85]
	v_mfma_f32_16x16x32_bf16 v[78:81], v[182:185], v[234:237], v[78:81]
	v_mfma_f32_16x16x32_bf16 v[122:125], v[186:189], v[202:205], v[122:125]
	v_mfma_f32_16x16x32_bf16 v[118:121], v[194:197], v[202:205], v[118:121]
	v_mfma_f32_16x16x32_bf16 v[106:109], v[186:189], v[210:213], v[106:109]
	v_mfma_f32_16x16x32_bf16 v[102:105], v[194:197], v[210:213], v[102:105]
	v_mfma_f32_16x16x32_bf16 v[90:93], v[186:189], v[222:225], v[90:93]
	v_mfma_f32_16x16x32_bf16 v[86:89], v[194:197], v[222:225], v[86:89]
	v_mfma_f32_16x16x32_bf16 v[74:77], v[186:189], v[230:233], v[74:77]
	v_mfma_f32_16x16x32_bf16 v[70:73], v[194:197], v[230:233], v[70:73]
	v_mfma_f32_16x16x32_bf16 v[122:125], v[190:193], v[206:209], v[122:125]
	v_mfma_f32_16x16x32_bf16 v[118:121], v[198:201], v[206:209], v[118:121]
	v_mfma_f32_16x16x32_bf16 v[106:109], v[190:193], v[218:221], v[106:109]
	v_mfma_f32_16x16x32_bf16 v[102:105], v[198:201], v[218:221], v[102:105]
	v_mfma_f32_16x16x32_bf16 v[90:93], v[190:193], v[226:229], v[90:93]
	v_mfma_f32_16x16x32_bf16 v[86:89], v[198:201], v[226:229], v[86:89]
	v_mfma_f32_16x16x32_bf16 v[74:77], v[190:193], v[234:237], v[74:77]
	v_mfma_f32_16x16x32_bf16 v[70:73], v[198:201], v[234:237], v[70:73]
	s_barrier
	s_add_i32 s26, s26, s20
	v_lshl_add_u64 v[148:149], s[42:43], 0, v[134:135]
	s_mov_b32 m0, s26
	ds_read_b128 v[202:205], v167 offset:16384
	ds_read_b128 v[206:209], v167 offset:17408
	ds_read_b128 v[210:213], v167 offset:18432
	ds_read_b128 v[218:221], v167 offset:19456
	ds_read_b128 v[222:225], v167 offset:20480
	ds_read_b128 v[226:229], v167 offset:21504
	ds_read_b128 v[230:233], v167 offset:22528
	ds_read_b128 v[234:237], v167 offset:23552
	global_load_lds_dwordx4 v[148:149], off
	s_add_i32 m0, s26, 0x2000
	s_add_u32 s34, s42, 0xb0000
	v_lshl_add_u64 v[160:161], s[42:43], 0, v[138:139]
	s_addc_u32 s35, s43, 0
	s_add_i32 s26, s27, s20
	global_load_lds_dwordx4 v[160:161], off
	v_lshl_add_u64 v[214:215], s[34:35], 0, v[134:135]
	s_mov_b32 m0, s26
	v_lshl_add_u64 v[238:239], s[44:45], 0, v[136:137]
	global_load_lds_dwordx4 v[214:215], off
	v_lshl_add_u64 v[214:215], s[34:35], 0, v[138:139]
	s_add_i32 m0, s26, 0x2000
	s_nop 0
	global_load_lds_dwordx4 v[214:215], off
	v_lshl_add_u64 v[214:215], s[44:45], 0, v[2:3]
	s_mov_b32 m0, s46
	s_nop 0
	global_load_lds_dwordx4 v[214:215], off
	s_mov_b32 m0, s47
	s_nop 0
	global_load_lds_dwordx4 v[238:239], off
	s_waitcnt vmcnt(8)
	s_waitcnt lgkmcnt(0)
	s_barrier
; #define PG8_STAGE(bufoff, gbase, voff) do { _Pragma("unroll") for (int _i = 0; _i < 2; ++_i) \
;         __builtin_amdgcn_global_load_lds((const unsigned*)((const char*)(gbase) + (voff)[_i]), (PG8_LAS unsigned*)(lds + (bufoff) + ldsw + _i * 8192), 16, 0, 0); } while (0)
; #define PG8_LDA(dst, b, h) do { _Pragma("unroll") for (int m = 0; m < 4; ++m) _Pragma("unroll") for (int k = 0; k < 2; ++k) dst[m][k] = *(const PG8_LAS bf16x8*)(lds + PG8_SA(b, h) + aoff + m * 2048 + k * 1024); } while (0)
; #define PG8_LDB(dst, b, h) do { _Pragma("unroll") for (int n = 0; n < 2; ++n) _Pragma("unroll") for (int k = 0; k < 2; ++k) dst[n][k] = *(const PG8_LAS bf16x8*)(lds + PG8_SB(b, h) + boff + n * 2048 + k * 1024); } while (0)
; #define PG8_MMA(ai, bj, At, Bt) do { __builtin_amdgcn_s_setprio(1); _Pragma("unroll") for (int m = 0; m < 4; ++m) _Pragma("unroll") for (int n = 0; n < 2; ++n) _Pragma("unroll") for (int k = 0; k < 2; ++k) \
;         acc[ai][bj][m][n] = __builtin_amdgcn_mfma_f32_16x16x32_bf16(Bt[n][k], At[m][k], acc[ai][bj][m][n], 0, 0, 0); __builtin_amdgcn_s_setprio(0); } while (0)
; #define PG8_WAIT_V(n) asm volatile("s_waitcnt vmcnt(" #n ")" ::: "memory")
; #define PG8_WAIT_L(n) asm volatile("s_waitcnt lgkmcnt(" #n ")" ::: "memory")
; #define PG8_BAR __builtin_amdgcn_s_barrier()
; #define PG8_SCHED __builtin_amdgcn_sched_barrier(0)
; template <class Epi, class Sched, bool ALIGN_EPI = false, bool SP2 = false>
; __device__ __forceinline__ void gemm_phase(PG8_LAS unsigned char* lds, const Gemm g, const Sched& S, const Epi& E, const int tid) {
;     ...
;             PG8_WAIT_V(8); PG8_WAIT_L(0); PG8_BAR; PG8_MMA(1, 0, At, B0); PG8_MMA(1, 1, At, B1); PG8_BAR; PG8_SCHED;
;             PG8_LDB(B0, 1, 0); PG8_LDB(B1, 1, 1); PG8_SCHED; PG8_LDA(At, 1, 0); PG8_STAGE(PG8_SA(0, 1), a2 + hstep, voffA);
;             PG8_WAIT_V(8); PG8_WAIT_L(0); PG8_BAR; PG8_MMA(0, 0, At, B0); PG8_MMA(0, 1, At, B1); PG8_BAR; PG8_SCHED;
	s_waitcnt lgkmcnt(0)
	v_mfma_f32_16x16x32_bf16 v[66:69], v[144:147], v[202:205], v[66:69]
	v_mfma_f32_16x16x32_bf16 v[62:65], v[178:181], v[202:205], v[62:65]
	v_mfma_f32_16x16x32_bf16 v[50:53], v[144:147], v[210:213], v[50:53]
	v_mfma_f32_16x16x32_bf16 v[46:49], v[178:181], v[210:213], v[46:49]
	v_mfma_f32_16x16x32_bf16 v[34:37], v[144:147], v[222:225], v[34:37]
	v_mfma_f32_16x16x32_bf16 v[30:33], v[178:181], v[222:225], v[30:33]
	v_mfma_f32_16x16x32_bf16 v[18:21], v[144:147], v[230:233], v[18:21]
	v_mfma_f32_16x16x32_bf16 v[14:17], v[178:181], v[230:233], v[14:17]
	v_mfma_f32_16x16x32_bf16 v[66:69], v[174:177], v[206:209], v[66:69]
	v_mfma_f32_16x16x32_bf16 v[62:65], v[182:185], v[206:209], v[62:65]
	v_mfma_f32_16x16x32_bf16 v[50:53], v[174:177], v[218:221], v[50:53]
	v_mfma_f32_16x16x32_bf16 v[46:49], v[182:185], v[218:221], v[46:49]
	v_mfma_f32_16x16x32_bf16 v[34:37], v[174:177], v[226:229], v[34:37]
	v_mfma_f32_16x16x32_bf16 v[30:33], v[182:185], v[226:229], v[30:33]
	v_mfma_f32_16x16x32_bf16 v[18:21], v[174:177], v[234:237], v[18:21]
	v_mfma_f32_16x16x32_bf16 v[14:17], v[182:185], v[234:237], v[14:17]
	v_mfma_f32_16x16x32_bf16 v[58:61], v[186:189], v[202:205], v[58:61]
	v_mfma_f32_16x16x32_bf16 v[54:57], v[194:197], v[202:205], v[54:57]
	v_mfma_f32_16x16x32_bf16 v[42:45], v[186:189], v[210:213], v[42:45]
	v_mfma_f32_16x16x32_bf16 v[38:41], v[194:197], v[210:213], v[38:41]
	v_mfma_f32_16x16x32_bf16 v[26:29], v[186:189], v[222:225], v[26:29]
	v_mfma_f32_16x16x32_bf16 v[22:25], v[194:197], v[222:225], v[22:25]
	v_mfma_f32_16x16x32_bf16 v[10:13], v[186:189], v[230:233], v[10:13]
	v_mfma_f32_16x16x32_bf16 v[6:9], v[194:197], v[230:233], v[6:9]
	v_mfma_f32_16x16x32_bf16 v[58:61], v[190:193], v[206:209], v[58:61]
	v_mfma_f32_16x16x32_bf16 v[54:57], v[198:201], v[206:209], v[54:57]
	v_mfma_f32_16x16x32_bf16 v[42:45], v[190:193], v[218:221], v[42:45]
	v_mfma_f32_16x16x32_bf16 v[38:41], v[198:201], v[218:221], v[38:41]
	v_mfma_f32_16x16x32_bf16 v[26:29], v[190:193], v[226:229], v[26:29]
	v_mfma_f32_16x16x32_bf16 v[22:25], v[198:201], v[226:229], v[22:25]
	v_mfma_f32_16x16x32_bf16 v[10:13], v[190:193], v[234:237], v[10:13]
	v_mfma_f32_16x16x32_bf16 v[6:9], v[198:201], v[234:237], v[6:9]
	s_barrier
	s_add_i32 s26, 0, 0x18000
	s_add_i32 s27, 0, 0x1c000
	v_add_u32_e32 v182, s26, v5
	v_add_u32_e32 v198, s27, v5
	ds_read_b128 v[144:147], v182
	ds_read_b128 v[174:177], v182 offset:1024
	ds_read_b128 v[178:181], v182 offset:2048
	ds_read_b128 v[182:185], v182 offset:3072
	ds_read_b128 v[186:189], v198
	ds_read_b128 v[190:193], v198 offset:1024
	ds_read_b128 v[194:197], v198 offset:2048
	ds_read_b128 v[198:201], v198 offset:3072
	s_add_u32 s34, s44, 0xb0000
	s_addc_u32 s35, s45, 0
	s_mov_b32 m0, s48
	v_lshl_add_u64 v[240:241], s[34:35], 0, v[2:3]
	ds_read_b128 v[202:205], v167 offset:32768
	ds_read_b128 v[206:209], v167 offset:33792
	ds_read_b128 v[210:213], v167 offset:34816
	ds_read_b128 v[218:221], v167 offset:35840
	ds_read_b128 v[222:225], v167 offset:36864
	ds_read_b128 v[226:229], v167 offset:37888
	ds_read_b128 v[230:233], v167 offset:38912
	ds_read_b128 v[234:237], v167 offset:39936
	global_load_lds_dwordx4 v[240:241], off
	v_lshl_add_u64 v[240:241], s[34:35], 0, v[136:137]
	s_mov_b32 m0, s49
	s_nop 0
	global_load_lds_dwordx4 v[240:241], off
	s_waitcnt vmcnt(8)
	s_waitcnt lgkmcnt(0)
	s_barrier
	s_waitcnt lgkmcnt(0)
	v_mfma_f32_16x16x32_bf16 v[130:133], v[144:147], v[202:205], v[130:133]
	v_mfma_f32_16x16x32_bf16 v[126:129], v[178:181], v[202:205], v[126:129]
	v_mfma_f32_16x16x32_bf16 v[114:117], v[144:147], v[210:213], v[114:117]
	v_mfma_f32_16x16x32_bf16 v[110:113], v[178:181], v[210:213], v[110:113]
	v_mfma_f32_16x16x32_bf16 v[98:101], v[144:147], v[222:225], v[98:101]
	v_mfma_f32_16x16x32_bf16 v[94:97], v[178:181], v[222:225], v[94:97]
	v_mfma_f32_16x16x32_bf16 v[82:85], v[144:147], v[230:233], v[82:85]
	v_mfma_f32_16x16x32_bf16 v[78:81], v[178:181], v[230:233], v[78:81]
	v_mfma_f32_16x16x32_bf16 v[130:133], v[174:177], v[206:209], v[130:133]
	v_mfma_f32_16x16x32_bf16 v[126:129], v[182:185], v[206:209], v[126:129]
	v_mfma_f32_16x16x32_bf16 v[114:117], v[174:177], v[218:221], v[114:117]
	v_mfma_f32_16x16x32_bf16 v[110:113], v[182:185], v[218:221], v[110:113]
	v_mfma_f32_16x16x32_bf16 v[98:101], v[174:177], v[226:229], v[98:101]
	v_mfma_f32_16x16x32_bf16 v[94:97], v[182:185], v[226:229], v[94:97]
	v_mfma_f32_16x16x32_bf16 v[82:85], v[174:177], v[234:237], v[82:85]
	v_mfma_f32_16x16x32_bf16 v[78:81], v[182:185], v[234:237], v[78:81]
	v_mfma_f32_16x16x32_bf16 v[122:125], v[186:189], v[202:205], v[122:125]
	v_mfma_f32_16x16x32_bf16 v[118:121], v[194:197], v[202:205], v[118:121]
	v_mfma_f32_16x16x32_bf16 v[106:109], v[186:189], v[210:213], v[106:109]
	v_mfma_f32_16x16x32_bf16 v[102:105], v[194:197], v[210:213], v[102:105]
	v_mfma_f32_16x16x32_bf16 v[90:93], v[186:189], v[222:225], v[90:93]
	v_mfma_f32_16x16x32_bf16 v[86:89], v[194:197], v[222:225], v[86:89]
	v_mfma_f32_16x16x32_bf16 v[74:77], v[186:189], v[230:233], v[74:77]
	v_mfma_f32_16x16x32_bf16 v[70:73], v[194:197], v[230:233], v[70:73]
	v_mfma_f32_16x16x32_bf16 v[122:125], v[190:193], v[206:209], v[122:125]
	v_mfma_f32_16x16x32_bf16 v[118:121], v[198:201], v[206:209], v[118:121]
	v_mfma_f32_16x16x32_bf16 v[106:109], v[190:193], v[218:221], v[106:109]
	v_mfma_f32_16x16x32_bf16 v[102:105], v[198:201], v[218:221], v[102:105]
	v_mfma_f32_16x16x32_bf16 v[90:93], v[190:193], v[226:229], v[90:93]
	v_mfma_f32_16x16x32_bf16 v[86:89], v[198:201], v[226:229], v[86:89]
	v_mfma_f32_16x16x32_bf16 v[74:77], v[190:193], v[234:237], v[74:77]
	v_mfma_f32_16x16x32_bf16 v[70:73], v[198:201], v[234:237], v[70:73]
	s_barrier
; #define PG8_STAGE(bufoff, gbase, voff) do { _Pragma("unroll") for (int _i = 0; _i < 2; ++_i) \
;         __builtin_amdgcn_global_load_lds((const unsigned*)((const char*)(gbase) + (voff)[_i]), (PG8_LAS unsigned*)(lds + (bufoff) + ldsw + _i * 8192), 16, 0, 0); } while (0)
; #define PG8_LDA(dst, b, h) do { _Pragma("unroll") for (int m = 0; m < 4; ++m) _Pragma("unroll") for (int k = 0; k < 2; ++k) dst[m][k] = *(const PG8_LAS bf16x8*)(lds + PG8_SA(b, h) + aoff + m * 2048 + k * 1024); } while (0)
; #define PG8_MMA(ai, bj, At, Bt) do { __builtin_amdgcn_s_setprio(1); _Pragma("unroll") for (int m = 0; m < 4; ++m) _Pragma("unroll") for (int n = 0; n < 2; ++n) _Pragma("unroll") for (int k = 0; k < 2; ++k) \
;         acc[ai][bj][m][n] = __builtin_amdgcn_mfma_f32_16x16x32_bf16(Bt[n][k], At[m][k], acc[ai][bj][m][n], 0, 0, 0); __builtin_amdgcn_s_setprio(0); } while (0)
; #define PG8_WAIT_V(n) asm volatile("s_waitcnt vmcnt(" #n ")" ::: "memory")
; #define PG8_WAIT_L(n) asm volatile("s_waitcnt lgkmcnt(" #n ")" ::: "memory")
; #define PG8_BAR __builtin_amdgcn_s_barrier()
; #define PG8_SCHED __builtin_amdgcn_sched_barrier(0)
; template <class Epi, class Sched, bool ALIGN_EPI = false, bool SP2 = false>
; __device__ __forceinline__ void gemm_phase(PG8_LAS unsigned char* lds, const Gemm g, const Sched& S, const Epi& E, const int tid) {
;     ...
;         for (int t = 0; t < nt; t += 2) {
;             const bool last = (t == nt - 2);
;             const char* a1 = cA + (size_t)(t + 1) * kstep;
;             const char* a2 = last ? nA : cA + (size_t)(t + 2) * kstep; const char* b2 = last ? nB : cB + (size_t)(t + 2) * kstep;
;             const char* a3 = a2 + kstep; const char* b3 = b2 + kstep;
;             if (last && has_next) S.a_ready(nxt);
;     ...
;             PG8_LDA(At, 1, 1); PG8_STAGE(PG8_SB(1, 0), b3, voffB); PG8_STAGE(PG8_SB(1, 1), b3 + hstep, voffB); PG8_STAGE(PG8_SA(1, 0), a3, voffA);
;             PG8_WAIT_V(8); PG8_WAIT_L(0); PG8_BAR; PG8_MMA(1, 0, At, B0); PG8_MMA(1, 1, At, B1); PG8_BAR; PG8_SCHED;
	s_add_i32 s26, s26, s20
	v_lshl_add_u64 v[148:149], v[148:149], 0, s[16:17]
	s_mov_b32 m0, s26
	ds_read_b128 v[202:205], v167 offset:49152
	ds_read_b128 v[206:209], v167 offset:50176
	ds_read_b128 v[210:213], v167 offset:51200
	ds_read_b128 v[218:221], v167 offset:52224
	ds_read_b128 v[222:225], v167 offset:53248
	ds_read_b128 v[226:229], v167 offset:54272
	ds_read_b128 v[230:233], v167 offset:55296
	ds_read_b128 v[234:237], v167 offset:56320
	global_load_lds_dwordx4 v[148:149], off
	s_add_i32 m0, s26, 0x2000
	s_add_u32 s34, s42, 0xb0080
	v_lshl_add_u64 v[148:149], v[160:161], 0, s[16:17]
	s_addc_u32 s35, s43, 0
	s_add_i32 s26, s27, s20
	global_load_lds_dwordx4 v[148:149], off
	v_lshl_add_u64 v[148:149], s[34:35], 0, v[134:135]
	s_mov_b32 m0, s26
	s_nop 0
	global_load_lds_dwordx4 v[148:149], off
	v_lshl_add_u64 v[148:149], s[34:35], 0, v[138:139]
	s_add_i32 m0, s26, 0x2000
	s_nop 0
	global_load_lds_dwordx4 v[148:149], off
	v_lshl_add_u64 v[148:149], v[214:215], 0, s[16:17]
	s_mov_b32 m0, s50
	s_nop 0
	global_load_lds_dwordx4 v[148:149], off
	v_lshl_add_u64 v[148:149], v[238:239], 0, s[16:17]
	s_mov_b32 m0, s51
	s_nop 0
	global_load_lds_dwordx4 v[148:149], off
	s_waitcnt vmcnt(8)
	s_waitcnt lgkmcnt(0)
	s_barrier
	s_waitcnt lgkmcnt(0)
	v_mfma_f32_16x16x32_bf16 v[66:69], v[144:147], v[202:205], v[66:69]
	v_mfma_f32_16x16x32_bf16 v[62:65], v[178:181], v[202:205], v[62:65]
	v_mfma_f32_16x16x32_bf16 v[50:53], v[144:147], v[210:213], v[50:53]
	v_mfma_f32_16x16x32_bf16 v[46:49], v[178:181], v[210:213], v[46:49]
	v_mfma_f32_16x16x32_bf16 v[34:37], v[144:147], v[222:225], v[34:37]
	v_mfma_f32_16x16x32_bf16 v[30:33], v[178:181], v[222:225], v[30:33]
	v_mfma_f32_16x16x32_bf16 v[18:21], v[144:147], v[230:233], v[18:21]
	v_mfma_f32_16x16x32_bf16 v[14:17], v[178:181], v[230:233], v[14:17]
	v_mfma_f32_16x16x32_bf16 v[66:69], v[174:177], v[206:209], v[66:69]
	v_mfma_f32_16x16x32_bf16 v[62:65], v[182:185], v[206:209], v[62:65]
	v_mfma_f32_16x16x32_bf16 v[50:53], v[174:177], v[218:221], v[50:53]
	v_mfma_f32_16x16x32_bf16 v[46:49], v[182:185], v[218:221], v[46:49]
	v_mfma_f32_16x16x32_bf16 v[34:37], v[174:177], v[226:229], v[34:37]
	v_mfma_f32_16x16x32_bf16 v[30:33], v[182:185], v[226:229], v[30:33]
	v_mfma_f32_16x16x32_bf16 v[18:21], v[174:177], v[234:237], v[18:21]
	v_mfma_f32_16x16x32_bf16 v[14:17], v[182:185], v[234:237], v[14:17]
	v_mfma_f32_16x16x32_bf16 v[58:61], v[186:189], v[202:205], v[58:61]
	v_mfma_f32_16x16x32_bf16 v[54:57], v[194:197], v[202:205], v[54:57]
	v_mfma_f32_16x16x32_bf16 v[42:45], v[186:189], v[210:213], v[42:45]
	v_mfma_f32_16x16x32_bf16 v[38:41], v[194:197], v[210:213], v[38:41]
	v_mfma_f32_16x16x32_bf16 v[26:29], v[186:189], v[222:225], v[26:29]
	v_mfma_f32_16x16x32_bf16 v[22:25], v[194:197], v[222:225], v[22:25]
	v_mfma_f32_16x16x32_bf16 v[10:13], v[186:189], v[230:233], v[10:13]
	v_mfma_f32_16x16x32_bf16 v[6:9], v[194:197], v[230:233], v[6:9]
	v_mfma_f32_16x16x32_bf16 v[58:61], v[190:193], v[206:209], v[58:61]
	v_mfma_f32_16x16x32_bf16 v[54:57], v[198:201], v[206:209], v[54:57]
	v_mfma_f32_16x16x32_bf16 v[42:45], v[190:193], v[218:221], v[42:45]
	v_mfma_f32_16x16x32_bf16 v[38:41], v[198:201], v[218:221], v[38:41]
	v_mfma_f32_16x16x32_bf16 v[26:29], v[190:193], v[226:229], v[26:29]
	v_mfma_f32_16x16x32_bf16 v[22:25], v[198:201], v[226:229], v[22:25]
	v_mfma_f32_16x16x32_bf16 v[10:13], v[190:193], v[234:237], v[10:13]
	v_mfma_f32_16x16x32_bf16 v[6:9], v[198:201], v[234:237], v[6:9]
	s_add_i32 s19, s19, 2
	s_add_u32 s1, s1, 0x100
	s_addc_u32 s18, s18, 0
	s_cmp_gt_u32 s19, 41
	s_mov_b64 s[38:39], s[40:41]
	s_barrier
	s_cbranch_scc0 .LBB0_792
	s_and_b64 vcc, exec, s[12:13]
	s_cbranch_vccz .LBB0_795
	s_barrier
